# v1 + NA loop-head vmcnt(0) moved to loop entry + P3 rgain loads hoisted to unit top, next-unit dec prefetch (no store wait at unit top)
# speedup vs baseline: 1.0444x; 1.0005x over previous
; #define LAS __attribute__((address_space(3)))
; __device__ __forceinline__ void na_strip(const Params& P, LAS unsigned char* lds, int strip, int hsel, int tid, int lane, int wave) {
;     ...
;     const int rsel = wave >> 2, nb = wave & 3;
;     const int g = lane >> 4, l15 = lane & 15, q4 = l15 >> 2, p = lane & 3;
;     const int kstart = nb == 0 ? 0 : (nb == 1 ? 8 : (nb == 2 ? 24 : 32));
;     const int qc = 16 * nb + l15, wsq = min(max(qc - 8, 0), 48);
;     const LAS float* rp = (const LAS float*)(lds + NA_RPB);
;     float msk[2][4]; int bofs[2][4];
; #pragma unroll
;     for (int kt = 0; kt < 2; ++kt)
; #pragma unroll
;         for (int i = 0; i < 4; ++i) { const int kc = kstart + 16 * kt + 4 * g + i; msk[kt][i] = ((kc >= wsq) && (kc < wsq + 16)) ? -NA_SHIFT : -INFINITY; bofs[kt][i] = min(max(kc - qc + 15, 0), 30); }
;     bf16x8 qf[2];
;     {   const size_t tq = (size_t)sq0 + (size_t)(r0 + rsel) * 64 + qc;
; #pragma unroll
;         for (int ks = 0; ks < 2; ++ks) qf[ks] = *(const bf16x8*)(QA + tq * 512 + h * 64 + 32 * ks + 8 * g); }
.LBB0_295:
	s_and_b64 s[4:5], s[4:5], exec
	s_waitcnt vmcnt(0)
	v_add_u32_e32 v4, s27, v105
	v_cmp_ge_u32_e32 vcc, v4, v104
	v_cmp_lt_u32_e64 s[4:5], v4, v106
	v_or_b32_e32 v5, 1, v4
	s_cselect_b32 s34, 4, 8
	s_and_b64 vcc, vcc, s[4:5]
	v_cmp_ge_u32_e64 s[4:5], v5, v104
	v_cmp_lt_u32_e64 s[6:7], v5, v106
	v_or_b32_e32 v6, 2, v4
	s_and_b64 s[4:5], s[4:5], s[6:7]
	v_cmp_ge_u32_e64 s[6:7], v6, v104
	v_cmp_lt_u32_e64 s[10:11], v6, v106
	v_or_b32_e32 v7, 3, v4
	s_and_b64 s[6:7], s[6:7], s[10:11]
	v_cmp_ge_u32_e64 s[10:11], v7, v104
	v_cmp_lt_u32_e64 s[12:13], v7, v106
	v_add_u32_e32 v8, 16, v4
	s_and_b64 s[10:11], s[10:11], s[12:13]
	v_cmp_ge_u32_e64 s[12:13], v8, v104
	v_cmp_lt_u32_e64 s[14:15], v4, v104
	v_add_u32_e32 v9, 17, v4
	s_and_b64 s[12:13], s[12:13], s[14:15]
	v_cmp_ge_u32_e64 s[14:15], v9, v104
	v_cmp_lt_u32_e64 s[16:17], v9, v106
	v_add_u32_e32 v10, 18, v4
	s_and_b64 s[14:15], s[14:15], s[16:17]
	v_cmp_ge_u32_e64 s[16:17], v10, v104
	v_cmp_lt_u32_e64 s[18:19], v10, v106
	v_add_u32_e32 v11, 19, v4
	s_and_b64 s[16:17], s[16:17], s[18:19]
	v_cmp_ge_u32_e64 s[18:19], v11, v104
	v_cmp_lt_u32_e64 s[20:21], v11, v106
	s_add_i32 s48, s76, s52
	s_and_b64 s[18:19], s[18:19], s[20:21]
	s_lshl_b64 s[20:21], s[48:49], 16
	v_add_u32_e32 v46, s26, v103
	s_add_u32 s20, s42, s20
	v_lshlrev_b32_e32 v70, 10, v46
	s_addc_u32 s21, s43, s21
	v_lshl_add_u64 v[2:3], s[20:21], 0, v[70:71]
	s_lshl_b32 s20, s25, 1
	s_mov_b32 s21, s49
	v_lshl_add_u64 v[2:3], v[2:3], 0, s[20:21]
	v_lshlrev_b32_e32 v70, 1, v68
	v_lshl_add_u64 v[2:3], v[2:3], 0, v[70:71]
	global_load_dwordx4 v[30:33], v[2:3], off
	global_load_dwordx4 v[26:29], v[2:3], off offset:64
	v_sub_u32_e32 v2, v4, v103
	v_max_i32_e32 v2, -15, v2
	v_add_u32_e32 v2, 15, v2
	v_min_u32_e32 v63, 30, v2
	v_sub_u32_e32 v2, v5, v103
	v_max_i32_e32 v2, -15, v2
	v_add_u32_e32 v2, 15, v2
	v_min_u32_e32 v65, 30, v2
	v_sub_u32_e32 v2, v6, v103
	v_max_i32_e32 v2, -15, v2
	v_add_u32_e32 v2, 15, v2
	v_min_u32_e32 v96, 30, v2
	v_sub_u32_e32 v2, v7, v103
	v_max_i32_e32 v2, -15, v2
	v_add_u32_e32 v2, 15, v2
	v_min_u32_e32 v98, 30, v2
	v_sub_u32_e32 v2, v8, v103
	v_max_i32_e32 v2, -15, v2
	v_add_u32_e32 v2, 15, v2
	v_min_u32_e32 v100, 30, v2
	v_sub_u32_e32 v2, v9, v103
	v_max_i32_e32 v2, -15, v2
	v_add_u32_e32 v2, 15, v2
	v_or_b32_e32 v3, s27, v87
	v_min_u32_e32 v155, 30, v2
	v_sub_u32_e32 v2, v10, v103
	v_add_u32_e32 v3, v3, v105
	v_max_i32_e32 v2, -15, v2
	v_lshlrev_b32_e32 v4, 1, v3
	v_cndmask_b32_e64 v64, v147, v148, s[4:5]
	v_add_u32_e32 v2, 15, v2
	v_and_b32_e32 v5, 12, v4
	s_add_i32 s4, 0, 0x12000
	v_min_u32_e32 v157, 30, v2
	v_sub_u32_e32 v2, v11, v103
	v_lshl_add_u32 v160, v3, 7, s4
	v_or_b32_e32 v3, v5, v102
	v_max_i32_e32 v2, -15, v2
	v_lshlrev_b32_e32 v161, 3, v3
	v_bitop3_b32 v3, v4, v108, 12 bitop3:0x6c
	v_add_u32_e32 v2, 15, v2
	v_lshlrev_b32_e32 v162, 3, v3
	v_bitop3_b32 v3, v4, v109, 12 bitop3:0x6c
	v_min_u32_e32 v159, 30, v2
	v_add_u32_e32 v2, s27, v85
	v_lshlrev_b32_e32 v163, 3, v3
	v_bitop3_b32 v3, v4, v110, 12 bitop3:0x6c
	v_cndmask_b32_e32 v62, v147, v148, vcc
	v_cndmask_b32_e64 v93, v147, v148, s[6:7]
	v_cndmask_b32_e64 v97, v147, v148, s[10:11]
	v_cndmask_b32_e64 v99, v147, v148, s[12:13]
	v_cndmask_b32_e64 v101, v147, v148, s[14:15]
	v_cndmask_b32_e64 v156, v147, v148, s[16:17]
	v_cndmask_b32_e64 v158, v147, v148, s[18:19]
	v_mov_b32_e32 v47, v71
	s_add_i32 s18, s34, -1
	v_lshl_add_u64 v[48:49], v[72:73], 0, s[20:21]
	v_lshl_add_u64 v[50:51], v[74:75], 0, s[20:21]
	v_lshlrev_b32_e32 v164, 3, v3
	v_lshl_add_u32 v165, v2, 7, 0
	s_mov_b32 s19, 0
	s_sub_i32 s20, 0, s48
	s_lshl_b32 s10, s25, 1
	s_mov_b32 s21, s48
	s_waitcnt vmcnt(0)
	s_branch .LBB0_297

; __device__ __forceinline__ void na_strip(const Params& P, LAS unsigned char* lds, int strip, int hsel, int tid, int lane, int wave) {
;     ...
;         const int r = r0 + 2 * pi, myr = r + rsel;
;         const size_t tq = (size_t)sq0 + (size_t)myr * 64 + qc;
;         const int lo = na_start(r, rows), lon = na_start(r + 2, rows);
;         const int nr0 = lo + 9, nr1 = lo + 10;
;         const bool need0 = (pi < npairs - 1) && (nr0 < lon + 9) && (nr0 < rows), need1 = (pi < npairs - 1) && (nr1 < lon + 9) && (nr1 < rows);
;         u32x4 nk0, nv0, nk1, nv1;
;         if (need0) { const size_t o = ((size_t)sq0 + (size_t)nr0 * 64) * 512 + ssrc; nk0 = *(const u32x4*)(KA + o); nv0 = *(const u32x4*)(VA + o); }
;         if (need1) { const size_t o = ((size_t)sq0 + (size_t)nr1 * 64) * 512 + ssrc; nk1 = *(const u32x4*)(KA + o); nv1 = *(const u32x4*)(VA + o); }
;         bf16x8 qn[2];
;         if (pi < npairs - 1) {
; #pragma unroll
;             for (int ks = 0; ks < 2; ++ks) qn[ks] = *(const bf16x8*)(QA + (tq + 128) * 512 + h * 64 + 32 * ks + 8 * g); }
.LBB0_301:
	s_add_i32 s48, s52, s76
	s_lshl_b64 s[26:27], s[48:49], 6
	v_lshl_add_u64 v[52:53], s[26:27], 0, v[46:47]
	v_mov_b64_e32 v[18:19], v[26:27]
	v_mov_b64_e32 v[22:23], v[30:31]
	v_lshlrev_b64 v[34:35], 10, v[52:53]
	s_andn2_b64 vcc, exec, s[16:17]
	v_mov_b64_e32 v[20:21], v[28:29]
	v_mov_b64_e32 v[24:25], v[32:33]
	s_cbranch_vccnz .LBB0_303
	v_lshl_add_u64 v[18:19], s[42:43], 0, v[34:35]
	s_mov_b32 s11, s49
	v_lshl_add_u64 v[18:19], v[18:19], 0, s[10:11]
	v_lshl_add_u64 v[18:19], v[18:19], 0, v[70:71]
	v_lshl_add_u64 v[20:21], v[18:19], 0, s[50:51]
	v_add_co_u32_e32 v18, vcc, 0x20000, v18
	s_nop 1
	v_addc_co_u32_e32 v19, vcc, 0, v19, vcc
	global_load_dwordx4 v[22:25], v[18:19], off
	s_nop 0
	global_load_dwordx4 v[18:21], v[20:21], off offset:64

; #define RT_LOAD(u_) do { const size_t tokc_ = (size_t)((u_) >> 2) * 128; const int h_ = (u_) & 3; \
;         _Pragma("unroll") for (int i = 0; i < 4; ++i) { const int idx = tid + 512 * i; const size_t src = (tokc_ + (idx >> 4)) * 512 + h_ * 128 + 8 * (idx & 15); \
;             rq[i] = *(const u32x4*)(QR + src); rk[i] = *(const u32x4*)(KR + src); rv[i] = *(const u32x4*)(VR + src); } } while (0)
; __device__ __forceinline__ void ret_phase(const Params& P, LAS unsigned char* lds, int tid, int lane, int wave, int bid, int G) {
;     ...
;     int u = bid; if (u >= RET_UNITS) return;
;     u32x4 rq[4], rk[4], rv[4];
;     ...
;     RT_LOAD(u);
;     for (; u < RET_UNITS; u += G) {
;         const int gc = u >> 2, h = u & 3; const size_t tokc = (size_t)gc * 128;
;         const float lgf2 = -__expf(P.dec_f[h]) * LOG2E, lgb2 = -__expf(P.dec_b[h]) * LOG2E;
.LBB0_380:
	s_cmp_lt_i32 s28, 5
	s_cselect_b64 s[6:7], -1, 0
	s_and_b64 s[0:1], s[6:7], s[0:1]
	s_andn2_b64 vcc, exec, s[0:1]
	s_cbranch_vccnz .LBB0_393
	s_cmpk_gt_i32 s2, 0x9ff
	s_cbranch_scc1 .LBB0_393
	s_add_u32 s10, s22, 0x20000000
	s_addc_u32 s11, s23, 0
	s_add_u32 s12, s22, 0x25000000
	s_addc_u32 s13, s23, 0
	s_add_u32 s14, s22, 0x2a000000
	s_addc_u32 s15, s23, 0
	s_add_u32 s21, s22, 0x2f000000
	s_addc_u32 s25, s23, 0
	s_add_u32 s44, s22, 0x34000000
	v_lshlrev_b32_e32 v1, 3, v0
	s_addc_u32 s45, s23, 0
	v_lshlrev_b32_e32 v74, 5, v0
	v_and_b32_e32 v106, 0x78, v1
	s_movk_i32 s0, 0x7e00
	v_mov_b32_e32 v1, 0x4000
	s_add_u32 s16, s22, 0x3e000000
	v_bitop3_b32 v110, v74, s0, v1 bitop3:0xc8
	s_mov_b32 s0, 0xfe00
	v_mov_b32_e32 v1, 0xc000
	s_addc_u32 s17, s23, 0
	v_bitop3_b32 v114, v74, s0, v1 bitop3:0xc8
	s_ashr_i32 s0, s2, 2
	s_ashr_i32 s1, s0, 31
	s_lshl_b32 s4, s2, 7
	s_lshl_b64 s[0:1], s[0:1], 16
	s_and_b32 s4, s4, 0x180
	s_or_b32 s0, s0, s4
	v_and_b32_e32 v108, 0x3e00, v74
	v_or_b32_e32 v1, s0, v106
	v_or_b32_e32 v2, v1, v108
	v_mov_b32_e32 v3, s1
	v_or_b32_e32 v112, 0x8000, v108
	v_lshlrev_b64 v[4:5], 1, v[2:3]
	v_or_b32_e32 v2, v1, v110
	v_lshl_add_u64 v[50:51], s[10:11], 0, v[4:5]
	v_lshl_add_u64 v[52:53], s[12:13], 0, v[4:5]
	v_lshl_add_u64 v[54:55], s[14:15], 0, v[4:5]
	v_lshlrev_b64 v[4:5], 1, v[2:3]
	v_or_b32_e32 v2, v1, v112
	v_lshl_add_u64 v[56:57], s[10:11], 0, v[4:5]
	v_lshl_add_u64 v[58:59], s[12:13], 0, v[4:5]
	v_lshl_add_u64 v[60:61], s[14:15], 0, v[4:5]
	v_lshlrev_b64 v[4:5], 1, v[2:3]
	v_or_b32_e32 v2, v1, v114
	v_lshlrev_b64 v[2:3], 1, v[2:3]
	v_lshl_add_u64 v[72:73], s[14:15], 0, v[2:3]
	v_lshl_add_u64 v[62:63], s[10:11], 0, v[4:5]
	v_lshl_add_u64 v[64:65], s[12:13], 0, v[4:5]
	v_lshl_add_u64 v[66:67], s[14:15], 0, v[4:5]
	v_lshl_add_u64 v[68:69], s[10:11], 0, v[2:3]
	v_lshl_add_u64 v[70:71], s[12:13], 0, v[2:3]
	global_load_dwordx4 v[42:45], v[72:73], off
	global_load_dwordx4 v[46:49], v[70:71], off
	global_load_dwordx4 v[38:41], v[68:69], off
	global_load_dwordx4 v[34:37], v[66:67], off
	global_load_dwordx4 v[26:29], v[64:65], off
	global_load_dwordx4 v[30:33], v[62:63], off
	global_load_dwordx4 v[18:21], v[60:61], off
	global_load_dwordx4 v[22:25], v[58:59], off
	global_load_dwordx4 v[14:17], v[56:57], off
	global_load_dwordx4 v[10:13], v[54:55], off
	global_load_dwordx4 v[2:5], v[52:53], off
	global_load_dwordx4 v[6:9], v[50:51], off
	v_lshrrev_b32_e32 v54, 2, v0
	v_and_b32_e32 v1, 15, v0
	v_bfe_u32 v50, v0, 6, 2
	v_and_b32_e32 v54, 12, v54
	v_bitop3_b32 v50, v54, v1, v50 bitop3:0x36
	v_lshlrev_b32_e32 v116, 4, v0
	v_lshlrev_b32_e32 v50, 4, v50
	s_movk_i32 s0, 0x1f00
	v_or_b32_e32 v54, 0x200, v0
	v_and_or_b32 v107, v116, s0, v50
	v_lshlrev_b32_e32 v55, 4, v54
	s_movk_i32 s0, 0x3f00
	v_lshlrev_b32_e32 v51, 1, v0
	v_and_or_b32 v109, v55, s0, v50
	v_or_b32_e32 v56, 0x6000, v116
	s_movk_i32 s0, 0x7f00
	v_and_b32_e32 v51, 14, v51
	v_and_or_b32 v111, v56, s0, v50
	v_lshrrev_b32_e32 v56, 1, v0
	v_bfe_u32 v52, v0, 5, 2
	v_or_b32_e32 v53, 1, v51
	v_and_b32_e32 v56, 12, v56
	v_bitop3_b32 v51, v56, v51, v52 bitop3:0x36
	v_bitop3_b32 v52, v56, v53, v52 bitop3:0x36
	v_and_b32_e32 v50, 0x3f00, v74
	v_lshlrev_b32_e32 v51, 4, v51
	v_lshlrev_b32_e32 v52, 4, v52
	v_lshlrev_b32_e32 v53, 5, v54
	v_mov_b32_e32 v115, 0
	v_or_b32_e32 v57, v51, v50
	v_or_b32_e32 v50, v52, v50
	v_and_b32_e32 v53, 0x7f00, v53
	v_or_b32_e32 v55, 0x4000, v107
	v_mov_b32_e32 v117, v115
	v_or_b32_e32 v51, v51, v53
	v_or_b32_e32 v52, v52, v53
	s_add_i32 s48, 0, 0x10000
	v_add_u32_e32 v129, 0, v50
	v_mbcnt_lo_u32_b32 v50, -1, 0
	s_lshl_b32 s46, s97, 4
	s_mov_b32 s19, 0
	s_mov_b32 s47, 0x8000
	v_lshrrev_b32_e32 v118, 4, v180
	v_bfe_u32 v113, v0, 2, 2
	v_and_b32_e32 v126, 3, v0
	v_lshl_add_u64 v[120:121], s[16:17], 0, v[116:117]
	v_add_u32_e32 v127, s48, v55
	s_movk_i32 s49, 0x2000
	s_mov_b32 s50, 0xa000
	s_add_i32 s51, 0, 0x18000
	s_mov_b32 s52, 0xc2fc0000
	v_add_u32_e32 v128, 0, v57
	v_add_u32_e32 v130, 0, v51
	v_add_u32_e32 v131, 0, v52
	s_movk_i32 s53, 0x3000
	s_brev_b32 s20, 60
	s_mov_b32 s24, 0x358637bd
	s_mov_b32 s54, 0x800000
	s_brev_b32 s55, 64
	v_mov_b32_e32 v132, 0x42800000
	v_not_b32_e32 v133, 63
	v_mbcnt_hi_u32_b32 v134, -1, v50
	s_mov_b32 s56, s2
	s_mov_b32 s26, s2
	s_and_b32 s57, s26, 3
	s_lshl_b32 s0, s57, 2
	v_mov_b32_e32 v50, s0
	global_load_dword v104, v50, s[58:59]
	global_load_dword v105, v50, s[60:61]
	v_add_u32_e32 v50, 0, v107
	v_add_u32_e32 v51, s48, v107
	s_waitcnt vmcnt(0)
	s_branch .Lp3_common
; #define LAS __attribute__((address_space(3)))
; __device__ __forceinline__ f32x4 mfma16(bf16x8 a, bf16x8 b, f32x4 c) { return __builtin_amdgcn_mfma_f32_16x16x32_bf16(a, b, c, 0, 0, 0); }
; __device__ __forceinline__ void ret_phase(const Params& P, LAS unsigned char* lds, int tid, int lane, int wave, int bid, int G) {
;     ...
;         f32x4 o[8];
; #pragma unroll
;         for (int t = 0; t < 8; ++t) o[t] = (f32x4){0.f, 0.f, 0.f, 0.f};
;         u32x4 grv[4];
; #pragma unroll
;         for (int it = 0; it < 4; ++it) grv[it] = *(const u32x4*)(GR + (tokc + w16 + 4 * it + g) * 512 + h * 128 + 8 * l15);
; #pragma unroll
;         for (int t = 0; t < 8; ++t)
; #pragma unroll
;             for (int ks = 0; ks < 4; ++ks) { o[t] = mfma16(qf[ks], *(const LAS bf16x8*)(Qt + off256(16 * t + l15, 4 * ks + g)), o[t]); }
;         float wb[4];
; #pragma unroll
;         for (int i = 0; i < 4; ++i) { const float pos = (float)(w16 + 4 * g + i); const float wf = exp2f(lgf2 * (pos + 1.f)); wb[i] = exp2f(lgb2 * (128.f - pos)); const float rt = wf / wb[i];
; #pragma unroll
;             for (int t = 0; t < 8; ++t) o[t][i] *= rt; }
.LBB0_383:
	s_waitcnt lgkmcnt(0)
	s_barrier
	s_ashr_i32 s41, s40, 31
	v_lshlrev_b32_e32 v66, 2, v1
	v_and_b32_e32 v86, 12, v66
	v_bfe_u32 v87, v1, 2, 2
	v_lshl_add_u32 v88, v1, 8, 0
	v_bitop3_b32 v66, v86, v118, v87 bitop3:0x36
	v_lshl_add_u32 v135, v66, 4, v88
	ds_read_b128 v[66:69], v135
	ds_read_b128 v[70:73], v135 offset:4096
	v_add_u32_e32 v74, 4, v118
	v_bitop3_b32 v74, v86, v74, v87 bitop3:0x36
	v_lshl_add_u32 v168, v74, 4, v88
	s_waitcnt lgkmcnt(1)
	v_mfma_f32_16x16x32_bf16 v[66:69], v[58:61], v[66:69], 0
	ds_read_b128 v[74:77], v168
	ds_read_b128 v[78:81], v168 offset:4096
	v_lshl_add_u32 v102, v118, 2, s46
	v_cvt_f32_i32_e32 v103, v102
	s_waitcnt lgkmcnt(1)
	v_mfma_f32_16x16x32_bf16 v[66:69], v[54:57], v[74:77], v[66:69]
	v_add_u32_e32 v74, 8, v118
	v_bitop3_b32 v74, v86, v74, v87 bitop3:0x36
	v_lshl_add_u32 v169, v74, 4, v88
	ds_read_b128 v[74:77], v169
	ds_read_b128 v[82:85], v169 offset:4096
	s_waitcnt lgkmcnt(1)
	v_mfma_f32_16x16x32_bf16 v[66:69], v[62:65], v[74:77], v[66:69]
	v_add_u32_e32 v74, 12, v118
	v_bitop3_b32 v74, v86, v74, v87 bitop3:0x36
	v_lshl_add_u32 v170, v74, 4, v88
	ds_read_b128 v[74:77], v170
	ds_read_b128 v[86:89], v170 offset:4096
	s_waitcnt lgkmcnt(1)
	v_mfma_f32_16x16x32_bf16 v[74:77], v[50:53], v[74:77], v[66:69]
	v_add_f32_e32 v119, 1.0, v103
	v_mul_f32_e32 v171, v105, v119
	v_cmp_gt_f32_e32 vcc, s52, v171
	v_mfma_f32_16x16x32_bf16 v[66:69], v[58:61], v[70:73], 0
	v_sub_f32_e32 v103, 0x43000000, v103
	v_cndmask_b32_e32 v171, 0, v133, vcc
	s_lshl_b64 s[40:41], s[40:41], 7
	v_mfma_f32_16x16x32_bf16 v[66:69], v[54:57], v[78:81], v[66:69]
	v_mfma_f32_16x16x32_bf16 v[66:69], v[62:65], v[82:85], v[66:69]
	s_waitcnt lgkmcnt(0)
	v_mfma_f32_16x16x32_bf16 v[70:73], v[50:53], v[86:89], v[66:69]
	s_nop 5
	ds_read_b128 v[66:69], v135 offset:8192
	ds_read_b128 v[78:81], v135 offset:12288
	ds_read_b128 v[82:85], v168 offset:8192
	ds_read_b128 v[86:89], v168 offset:12288
	s_waitcnt lgkmcnt(3)
	v_mfma_f32_16x16x32_bf16 v[66:69], v[58:61], v[66:69], 0
	s_waitcnt lgkmcnt(1)
	v_mfma_f32_16x16x32_bf16 v[66:69], v[54:57], v[82:85], v[66:69]
	ds_read_b128 v[82:85], v169 offset:8192
	ds_read_b128 v[90:93], v169 offset:12288
	s_waitcnt lgkmcnt(1)
	v_mfma_f32_16x16x32_bf16 v[66:69], v[62:65], v[82:85], v[66:69]
	ds_read_b128 v[82:85], v170 offset:8192
	ds_read_b128 v[94:97], v170 offset:12288
	ds_read_b128 v[98:101], v135 offset:16384
	ds_read_b128 v[122:125], v135 offset:20480
	s_waitcnt lgkmcnt(3)
	v_mfma_f32_16x16x32_bf16 v[82:85], v[50:53], v[82:85], v[66:69]
	v_mfma_f32_16x16x32_bf16 v[66:69], v[58:61], v[78:81], 0
	v_mfma_f32_16x16x32_bf16 v[66:69], v[54:57], v[86:89], v[66:69]
	ds_read_b128 v[86:89], v168 offset:16384
	ds_read_b128 v[136:139], v168 offset:20480
	ds_read_b128 v[140:143], v169 offset:16384
	ds_read_b128 v[144:147], v169 offset:20480
	v_mfma_f32_16x16x32_bf16 v[66:69], v[62:65], v[90:93], v[66:69]
	ds_read_b128 v[90:93], v170 offset:16384
	ds_read_b128 v[148:151], v170 offset:20480
	ds_read_b128 v[152:155], v135 offset:24576
	ds_read_b128 v[156:159], v135 offset:28672
	s_waitcnt lgkmcnt(10)
	v_mfma_f32_16x16x32_bf16 v[78:81], v[50:53], v[94:97], v[66:69]
	s_nop 2
	ds_read_b128 v[66:69], v168 offset:24576
	ds_read_b128 v[160:163], v168 offset:28672
	s_waitcnt lgkmcnt(11)
	v_mfma_f32_16x16x32_bf16 v[94:97], v[58:61], v[98:101], 0
	ds_read_b128 v[98:101], v169 offset:24576
	ds_read_b128 v[164:167], v169 offset:28672
	s_waitcnt lgkmcnt(11)
	v_mfma_f32_16x16x32_bf16 v[86:89], v[54:57], v[86:89], v[94:97]
	s_nop 3
	v_cndmask_b32_e32 v94, 0, v132, vcc
	v_fmac_f32_e32 v94, v105, v119
	v_exp_f32_e32 v119, v94
	s_waitcnt lgkmcnt(9)
	v_mfma_f32_16x16x32_bf16 v[86:89], v[62:65], v[140:143], v[86:89]
	ds_read_b128 v[94:97], v170 offset:24576
	ds_read_b128 v[140:143], v170 offset:28672
	v_ldexp_f32 v119, v119, v171
	v_mul_f32_e32 v171, v104, v103
	v_cmp_gt_f32_e32 vcc, s52, v171
	s_waitcnt lgkmcnt(9)
	v_mfma_f32_16x16x32_bf16 v[90:93], v[50:53], v[90:93], v[86:89]
	v_mfma_f32_16x16x32_bf16 v[86:89], v[58:61], v[122:125], 0
	v_cndmask_b32_e32 v122, 0, v132, vcc
	v_fmac_f32_e32 v122, v104, v103
	v_or_b32_e32 v103, 1, v102
	v_cvt_f32_i32_e32 v103, v103
	v_cndmask_b32_e32 v123, 0, v133, vcc
	v_mfma_f32_16x16x32_bf16 v[86:89], v[54:57], v[136:139], v[86:89]
	v_exp_f32_e32 v122, v122
	v_add_f32_e32 v124, 1.0, v103
	v_mul_f32_e32 v125, v105, v124
	v_cmp_gt_f32_e32 vcc, s52, v125
	s_waitcnt lgkmcnt(7)
	v_mfma_f32_16x16x32_bf16 v[136:139], v[58:61], v[152:155], 0
	v_ldexp_f32 v122, v122, v123
	v_cndmask_b32_e32 v125, 0, v132, vcc
	v_fmac_f32_e32 v125, v105, v124
	v_exp_f32_e32 v124, v125
	s_waitcnt lgkmcnt(5)
	v_mfma_f32_16x16x32_bf16 v[66:69], v[54:57], v[66:69], v[136:139]
	v_cndmask_b32_e32 v123, 0, v133, vcc
	v_sub_f32_e32 v103, 0x43000000, v103
	v_ldexp_f32 v124, v124, v123
	v_mul_f32_e32 v123, v104, v103
	v_cmp_gt_f32_e32 vcc, s52, v123
	s_waitcnt lgkmcnt(3)
	v_mfma_f32_16x16x32_bf16 v[66:69], v[62:65], v[98:101], v[66:69]
	v_div_scale_f32 v99, s[0:1], v122, v122, v119
	v_cndmask_b32_e32 v98, 0, v132, vcc
	v_fmac_f32_e32 v98, v104, v103
	v_exp_f32_e32 v98, v98
	v_rcp_f32_e32 v100, v99
	v_cndmask_b32_e32 v101, 0, v133, vcc
	s_waitcnt lgkmcnt(1)
; #define LAS __attribute__((address_space(3)))
; __device__ __forceinline__ f32x4 mfma16(bf16x8 a, bf16x8 b, f32x4 c) { return __builtin_amdgcn_mfma_f32_16x16x32_bf16(a, b, c, 0, 0, 0); }
; __device__ __forceinline__ void ret_phase(const Params& P, LAS unsigned char* lds, int tid, int lane, int wave, int bid, int G) {
;     ...
;         for (int t = 0; t < 8; ++t)
; #pragma unroll
;             for (int ks = 0; ks < 4; ++ks) { o[t] = mfma16(qf[ks], *(const LAS bf16x8*)(Qt + off256(16 * t + l15, 4 * ks + g)), o[t]); }
;         float wb[4];
; #pragma unroll
;         for (int i = 0; i < 4; ++i) { const float pos = (float)(w16 + 4 * g + i); const float wf = exp2f(lgf2 * (pos + 1.f)); wb[i] = exp2f(lgb2 * (128.f - pos)); const float rt = wf / wb[i];
; #pragma unroll
;             for (int t = 0; t < 8; ++t) o[t][i] *= rt; }
; #pragma unroll
;         for (int t = 0; t < 8; ++t)
; #pragma unroll
;             for (int ks = 0; ks < 4; ++ks) { o[t] = mfma16(qf[ks], *(const LAS bf16x8*)(Kt + off256(16 * t + l15, 4 * ks + g)), o[t]); }
; #pragma unroll
;         for (int i = 0; i < 4; ++i)
; #pragma unroll
;             for (int t = 0; t < 8; ++t) o[t][i] *= wb[i];
	v_mfma_f32_16x16x32_bf16 v[94:97], v[50:53], v[94:97], v[66:69]
	v_ldexp_f32 v123, v98, v101
	v_fma_f32 v98, -v99, v100, 1.0
	v_fmac_f32_e32 v100, v98, v100
	v_div_scale_f32 v98, vcc, v119, v122, v119
	v_mul_f32_e32 v101, v98, v100
	v_fma_f32 v103, -v99, v101, v98
	v_fmac_f32_e32 v101, v103, v100
	v_fma_f32 v98, -v99, v101, v98
	v_div_scale_f32 v99, s[0:1], v123, v123, v124
	v_rcp_f32_e32 v103, v99
	v_div_fmas_f32 v98, v98, v100, v101
	v_div_fixup_f32 v98, v98, v122, v119
	v_mfma_f32_16x16x32_bf16 v[66:69], v[58:61], v[156:159], 0
	v_fma_f32 v100, -v99, v103, 1.0
	v_fmac_f32_e32 v103, v100, v103
	v_div_scale_f32 v100, vcc, v124, v123, v124
	v_mul_f32_e32 v101, v100, v103
	v_fma_f32 v119, -v99, v101, v100
	v_fmac_f32_e32 v101, v119, v103
	v_fma_f32 v99, -v99, v101, v100
	v_or_b32_e32 v100, 2, v102
	v_cvt_f32_i32_e32 v100, v100
	v_div_fmas_f32 v99, v99, v103, v101
	v_or_b32_e32 v102, 3, v102
	v_cvt_f32_i32_e32 v102, v102
	v_add_f32_e32 v101, 1.0, v100
	v_mul_f32_e32 v103, v105, v101
	v_cmp_gt_f32_e32 vcc, s52, v103
	v_sub_f32_e32 v100, 0x43000000, v100
	v_mul_f32_e32 v119, v104, v100
	v_cndmask_b32_e32 v103, 0, v132, vcc
	v_fmac_f32_e32 v103, v105, v101
	v_exp_f32_e32 v101, v103
	v_cndmask_b32_e32 v103, 0, v133, vcc
	v_cmp_gt_f32_e32 vcc, s52, v119
	v_div_fixup_f32 v99, v99, v123, v124
	v_mfma_f32_16x16x32_bf16 v[66:69], v[54:57], v[160:163], v[66:69]
	v_cndmask_b32_e32 v119, 0, v132, vcc
	v_fmac_f32_e32 v119, v104, v100
	v_exp_f32_e32 v100, v119
	v_add_f32_e32 v119, 1.0, v102
	v_mul_f32_e32 v124, v105, v119
	v_cmp_gt_f32_e64 s[0:1], s52, v124
	v_sub_f32_e32 v102, 0x43000000, v102
	v_mfma_f32_16x16x32_bf16 v[66:69], v[62:65], v[164:167], v[66:69]
	v_cndmask_b32_e64 v124, 0, v132, s[0:1]
	v_fmac_f32_e32 v124, v105, v119
	v_mul_f32_e32 v119, v104, v102
	v_cmp_gt_f32_e64 s[4:5], s52, v119
	v_exp_f32_e32 v105, v124
	ds_read_b128 v[136:139], v135 offset:36864
	v_cndmask_b32_e64 v119, 0, v132, s[4:5]
	v_fmac_f32_e32 v119, v104, v102
	v_exp_f32_e32 v102, v119
	v_cndmask_b32_e64 v104, 0, v133, s[0:1]
	v_ldexp_f32 v104, v105, v104
	v_cndmask_b32_e64 v105, 0, v133, s[4:5]
	v_ldexp_f32 v125, v102, v105
	v_div_scale_f32 v102, s[0:1], v125, v125, v104
	v_rcp_f32_e32 v105, v102
	v_ldexp_f32 v119, v101, v103
	v_cndmask_b32_e32 v101, 0, v133, vcc
	v_ldexp_f32 v124, v100, v101
	v_fma_f32 v100, -v102, v105, 1.0
	v_fmac_f32_e32 v105, v100, v105
	v_div_scale_f32 v100, vcc, v104, v125, v104
	v_mul_f32_e32 v101, v100, v105
	v_fma_f32 v103, -v102, v101, v100
	v_fmac_f32_e32 v101, v103, v105
	v_fma_f32 v100, -v102, v101, v100
	v_div_scale_f32 v102, s[0:1], v124, v124, v119
	v_rcp_f32_e32 v103, v102
	v_div_fmas_f32 v100, v100, v105, v101
	v_div_fixup_f32 v157, v100, v125, v104
	v_pk_mul_f32 v[74:75], v[98:99], v[74:75]
	v_fma_f32 v100, -v102, v103, 1.0
	v_fmac_f32_e32 v103, v100, v103
	v_div_scale_f32 v100, vcc, v119, v124, v119
	v_mul_f32_e32 v101, v100, v103
	v_fma_f32 v104, -v102, v101, v100
	v_fmac_f32_e32 v101, v104, v103
	v_fma_f32 v100, -v102, v101, v100
	v_div_fmas_f32 v104, v100, v103, v101
	ds_read_b128 v[100:103], v135 offset:32768
	v_div_fixup_f32 v156, v104, v124, v119
	v_pk_mul_f32 v[76:77], v[156:157], v[76:77]
	s_waitcnt lgkmcnt(2)
	v_mfma_f32_16x16x32_bf16 v[66:69], v[50:53], v[140:143], v[66:69]
	v_mul_f32_e64 v72, v156, v72
	v_mul_f32_e64 v73, v157, v73
	v_pk_mul_f32 v[70:71], v[98:99], v[70:71]
	v_pk_mul_f32 v[96:97], v[156:157], v[96:97]
	s_waitcnt lgkmcnt(0)
	v_mfma_f32_16x16x32_bf16 v[74:77], v[58:61], v[100:103], v[74:77]
	ds_read_b128 v[100:103], v168 offset:32768
	ds_read_b128 v[140:143], v168 offset:36864
	v_pk_mul_f32 v[94:95], v[98:99], v[94:95]
	s_add_u32 s0, s40, s46
	v_mfma_f32_16x16x32_bf16 v[70:73], v[58:61], v[136:139], v[70:73]
	s_addc_u32 s1, s41, 0
	v_ashrrev_i32_e32 v119, 31, v118
	s_lshl_b32 s18, s57, 8
	v_mfma_f32_16x16x32_bf16 v[86:89], v[62:65], v[144:147], v[86:89]
	v_mul_f32_e64 v68, v156, v68
	v_mul_f32_e64 v69, v157, v69
	v_pk_mul_f32 v[66:67], v[98:99], v[66:67]
	v_lshlrev_b32_e32 v152, 3, v1
	s_waitcnt lgkmcnt(1)
	v_mfma_f32_16x16x32_bf16 v[74:77], v[54:57], v[100:103], v[74:77]
	ds_read_b128 v[100:103], v169 offset:32768
	ds_read_b128 v[144:147], v169 offset:36864
	v_ashrrev_i32_e32 v153, 31, v152
	s_waitcnt lgkmcnt(2)
	v_mfma_f32_16x16x32_bf16 v[70:73], v[54:57], v[140:143], v[70:73]
	v_mfma_f32_16x16x32_bf16 v[86:89], v[50:53], v[148:151], v[86:89]
	s_waitcnt lgkmcnt(1)
	v_mfma_f32_16x16x32_bf16 v[74:77], v[62:65], v[100:103], v[74:77]
	ds_read_b128 v[100:103], v170 offset:32768
	ds_read_b128 v[148:151], v170 offset:36864
	ds_read_b128 v[136:139], v135 offset:40960
	ds_read_b128 v[140:143], v135 offset:45056
	s_waitcnt lgkmcnt(4)
	v_mfma_f32_16x16x32_bf16 v[70:73], v[62:65], v[144:147], v[70:73]
	s_waitcnt lgkmcnt(3)
	v_mfma_f32_16x16x32_bf16 v[102:105], v[50:53], v[100:103], v[74:77]
	v_lshl_add_u64 v[100:101], s[0:1], 0, v[118:119]
	s_add_u32 s0, s21, s18
	s_addc_u32 s1, s25, 0
	s_waitcnt lgkmcnt(2)
	v_mfma_f32_16x16x32_bf16 v[74:77], v[50:53], v[148:151], v[70:73]
	v_lshl_add_u64 v[158:159], v[152:153], 1, s[0:1]
	v_lshlrev_b64 v[100:101], 10, v[100:101]
	s_nop 0
	v_pk_mul_f32 v[104:105], v[124:125], v[104:105]
	v_pk_mul_f32 v[72:73], v[156:157], v[84:85]
	v_pk_mul_f32 v[70:71], v[98:99], v[82:83]
	v_pk_mul_f32 v[102:103], v[122:123], v[102:103]
	s_nop 0
	v_pk_mul_f32 v[76:77], v[124:125], v[76:77]
	s_waitcnt lgkmcnt(1)
	v_mfma_f32_16x16x32_bf16 v[70:73], v[58:61], v[136:139], v[70:73]
	ds_read_b128 v[82:85], v168 offset:40960
	ds_read_b128 v[136:139], v168 offset:45056
	v_pk_mul_f32 v[74:75], v[122:123], v[74:75]
	s_add_i32 s56, s56, s3
	s_waitcnt lgkmcnt(1)
; #define LAS __attribute__((address_space(3)))
; __device__ __forceinline__ s16x4 tr_read(const LAS unsigned char* p) { return __builtin_amdgcn_ds_read_tr16_b64_v4i16((LAS s16x4*)p); }
; __device__ __forceinline__ bf16x8 cat8(s16x4 a, s16x4 b) { return (bf16x8){a[0], a[1], a[2], a[3], b[0], b[1], b[2], b[3]}; }
; __device__ __forceinline__ f32x4 mfma16(bf16x8 a, bf16x8 b, f32x4 c) { return __builtin_amdgcn_mfma_f32_16x16x32_bf16(a, b, c, 0, 0, 0); }
; #define OPQ_ALL() do { asm volatile("" : "+v"(g), "+v"(l15), "+v"(q4), "+v"(p)); } while (0)
; __device__ __forceinline__ void ret_phase(const Params& P, LAS unsigned char* lds, int tid, int lane, int wave, int bid, int G) {
;     ...
;         for (int it = 0; it < 4; ++it) grv[it] = *(const u32x4*)(GR + (tokc + w16 + 4 * it + g) * 512 + h * 128 + 8 * l15);
;     ...
;         for (int t = 0; t < 8; ++t)
; #pragma unroll
;             for (int ks = 0; ks < 4; ++ks) { o[t] = mfma16(qf[ks], *(const LAS bf16x8*)(Kt + off256(16 * t + l15, 4 * ks + g)), o[t]); }
; #pragma unroll
;         for (int i = 0; i < 4; ++i)
; #pragma unroll
;             for (int t = 0; t < 8; ++t) o[t][i] *= wb[i];
;         OPQ_ALL();
; #pragma unroll
;         for (int ks = 0; ks < 4; ++ks) {
;             const bf16x8 pa = *(const LAS bf16x8*)(Pt + off256(w16 + l15, 4 * ks + g));
;             const unsigned r0 = 32 * ks + 8 * g + q4, r1 = r0 + 4;
; #pragma unroll
;             for (int t = 0; t < 8; ++t) { const unsigned ch = 2 * t + (p >> 1);
;                 const bf16x8 vb = cat8(tr_read(Vt + off256(r0, ch) + 8 * (p & 1)), tr_read(Vt + off256(r1, ch) + 8 * (p & 1)));
;                 o[t] = mfma16(pa, vb, o[t]); }
	v_mfma_f32_16x16x32_bf16 v[70:73], v[54:57], v[82:85], v[70:73]
	ds_read_b128 v[82:85], v169 offset:40960
	ds_read_b128 v[144:147], v169 offset:45056
	s_waitcnt lgkmcnt(1)
	v_mfma_f32_16x16x32_bf16 v[70:73], v[62:65], v[82:85], v[70:73]
	ds_read_b128 v[82:85], v170 offset:40960
	ds_read_b128 v[148:151], v170 offset:45056
	s_waitcnt lgkmcnt(1)
	v_mfma_f32_16x16x32_bf16 v[82:85], v[50:53], v[82:85], v[70:73]
	s_nop 3
	v_mul_f32_e64 v72, v156, v80
	v_mul_f32_e64 v73, v157, v81
	v_pk_mul_f32 v[70:71], v[98:99], v[78:79]
	s_nop 0
	v_pk_mul_f32 v[84:85], v[124:125], v[84:85]
	v_pk_mul_f32 v[82:83], v[122:123], v[82:83]
	v_mfma_f32_16x16x32_bf16 v[70:73], v[58:61], v[140:143], v[70:73]
	ds_read_b128 v[140:143], v135 offset:53248
	v_mfma_f32_16x16x32_bf16 v[70:73], v[54:57], v[136:139], v[70:73]
	ds_read_b128 v[136:139], v135 offset:49152
	v_mfma_f32_16x16x32_bf16 v[70:73], v[62:65], v[144:147], v[70:73]
	s_waitcnt lgkmcnt(2)
	v_mfma_f32_16x16x32_bf16 v[78:81], v[50:53], v[148:151], v[70:73]
	s_nop 5
	v_mul_f32_e64 v72, v156, v92
	v_mul_f32_e64 v73, v157, v93
	v_pk_mul_f32 v[70:71], v[98:99], v[90:91]
	v_pk_mul_f32 v[80:81], v[124:125], v[80:81]
	v_pk_mul_f32 v[78:79], v[122:123], v[78:79]
	s_waitcnt lgkmcnt(0)
	v_mfma_f32_16x16x32_bf16 v[70:73], v[58:61], v[136:139], v[70:73]
	ds_read_b128 v[90:93], v168 offset:49152
	ds_read_b128 v[136:139], v168 offset:53248
	s_waitcnt lgkmcnt(1)
	v_mfma_f32_16x16x32_bf16 v[70:73], v[54:57], v[90:93], v[70:73]
	ds_read_b128 v[90:93], v169 offset:49152
	ds_read_b128 v[144:147], v169 offset:53248
	s_waitcnt lgkmcnt(1)
	v_mfma_f32_16x16x32_bf16 v[70:73], v[62:65], v[90:93], v[70:73]
	ds_read_b128 v[90:93], v170 offset:49152
	ds_read_b128 v[148:151], v170 offset:53248
	s_waitcnt lgkmcnt(1)
	v_mfma_f32_16x16x32_bf16 v[90:93], v[50:53], v[90:93], v[70:73]
	s_nop 3
	v_mul_f32_e64 v72, v156, v88
	v_mul_f32_e64 v73, v157, v89
	v_pk_mul_f32 v[70:71], v[98:99], v[86:87]
	s_nop 0
	v_pk_mul_f32 v[92:93], v[124:125], v[92:93]
	v_pk_mul_f32 v[90:91], v[122:123], v[90:91]
	v_mfma_f32_16x16x32_bf16 v[70:73], v[58:61], v[140:143], v[70:73]
	v_mfma_f32_16x16x32_bf16 v[70:73], v[54:57], v[136:139], v[70:73]
	v_mfma_f32_16x16x32_bf16 v[70:73], v[62:65], v[144:147], v[70:73]
	s_waitcnt lgkmcnt(0)
	v_mfma_f32_16x16x32_bf16 v[86:89], v[50:53], v[148:151], v[70:73]
	s_nop 5
	ds_read_b128 v[70:73], v135 offset:57344
	ds_read_b128 v[136:139], v168 offset:57344
	ds_read_b128 v[140:143], v135 offset:61440
	s_waitcnt lgkmcnt(2)
	v_mfma_f32_16x16x32_bf16 v[70:73], v[58:61], v[70:73], v[94:97]
	s_nop 2
	ds_read_b128 v[94:97], v169 offset:57344
	ds_read_b128 v[144:147], v168 offset:61440
	v_pk_mul_f32 v[88:89], v[124:125], v[88:89]
	v_pk_mul_f32 v[86:87], v[122:123], v[86:87]
	s_waitcnt lgkmcnt(3)
	v_mfma_f32_16x16x32_bf16 v[70:73], v[54:57], v[136:139], v[70:73]
	ds_read_b128 v[136:139], v170 offset:57344
	ds_read_b128 v[148:151], v169 offset:61440
	ds_read_b128 v[152:155], v170 offset:61440
	s_waitcnt lgkmcnt(4)
	v_mfma_f32_16x16x32_bf16 v[70:73], v[62:65], v[94:97], v[70:73]
	s_waitcnt lgkmcnt(2)
	v_mfma_f32_16x16x32_bf16 v[94:97], v[50:53], v[136:139], v[70:73]
	v_lshl_add_u64 v[136:137], v[158:159], 0, v[100:101]
	v_mfma_f32_16x16x32_bf16 v[70:73], v[58:61], v[140:143], v[66:69]
	v_add_co_u32_e32 v58, vcc, s49, v136
	s_nop 4
	v_pk_mul_f32 v[96:97], v[124:125], v[96:97]
	v_mfma_f32_16x16x32_bf16 v[98:101], v[54:57], v[144:147], v[70:73]
	v_addc_co_u32_e32 v59, vcc, 0, v137, vcc
	v_add_co_u32_e32 v54, vcc, s53, v136
	global_load_dwordx4 v[66:69], v[58:59], off offset:-4096
	s_nop 0
	global_load_dwordx4 v[58:61], v[58:59], off
	v_addc_co_u32_e32 v55, vcc, 0, v137, vcc
	global_load_dwordx4 v[70:73], v[136:137], off
	s_nop 0
	global_load_dwordx4 v[54:57], v[54:55], off
	s_waitcnt lgkmcnt(1)
	v_mfma_f32_16x16x32_bf16 v[142:145], v[62:65], v[148:151], v[98:101]
	v_mul_f32_e64 v94, v122, v94
	v_mul_f32_e64 v95, v123, v95
	v_add_u32_e32 v62, s46, v1
	v_lshl_add_u32 v139, v62, 8, s51
	v_lshlrev_b32_e32 v62, 2, v113
	v_lshl_add_u32 v137, v118, 3, v113
	v_and_b32_e32 v119, 12, v62
	v_lshlrev_b32_e32 v62, 3, v126
	v_lshlrev_b32_e32 v63, 2, v1
	v_and_b32_e32 v62, 8, v62
	v_add_u32_e32 v64, 4, v137
	v_and_b32_e32 v136, 12, v63
	v_bfe_u32 v138, v1, 2, 2
	v_ashrrev_i32_e32 v135, 1, v126
	v_add_u32_e32 v140, s48, v62
	v_bfe_u32 v151, v64, 2, 2
	v_bfe_u32 v141, v137, 2, 2
	v_bitop3_b32 v63, v136, v118, v138 bitop3:0x36
	v_lshl_add_u32 v156, v64, 8, v140
	v_bitop3_b32 v100, v151, v135, v119 bitop3:0x36
	v_bitop3_b32 v62, v141, v135, v119 bitop3:0x36
	v_lshl_add_u32 v63, v63, 4, v139
	v_lshl_add_u32 v150, v137, 8, v140
	v_lshl_add_u32 v100, v100, 4, v156
	v_lshl_add_u32 v157, v62, 4, v150
	ds_read_b128 v[62:65], v63
	ds_read_b64_tr_b16 v[98:99], v157
	ds_read_b64_tr_b16 v[100:101], v100
	v_add_u32_e32 v170, 2, v135
	s_waitcnt lgkmcnt(3)
	v_mfma_f32_16x16x32_bf16 v[50:53], v[50:53], v[152:155], v[142:145]
	v_add_u32_e32 v171, 4, v135
	v_add_u32_e32 v200, 6, v135
	v_add_u32_e32 v201, 8, v135
	ds_read_b64_tr_b16 v[142:143], v157 offset:24576
	s_waitcnt lgkmcnt(1)
	v_mfma_f32_16x16x32_bf16 v[98:101], v[62:65], v[98:101], v[102:105]
	v_add_u32_e32 v202, 10, v135
	v_add_u32_e32 v203, 12, v135
	v_add_u32_e32 v204, 14, v135
	v_bitop3_b32 v102, v141, v170, v119 bitop3:0x36
	v_lshl_add_u32 v146, v102, 4, v150
	ds_read_b64_tr_b16 v[102:103], v146
	v_bitop3_b32 v104, v151, v170, v119 bitop3:0x36
	v_lshl_add_u32 v104, v104, 4, v156
	v_bitop3_b32 v105, v141, v171, v119 bitop3:0x36
	v_lshl_add_u32 v160, v105, 4, v150
	ds_read_b64_tr_b16 v[104:105], v104
	ds_read_b64_tr_b16 v[144:145], v160
	ds_read_b64_tr_b16 v[148:149], v160 offset:8192
	ds_read_b64_tr_b16 v[152:153], v160 offset:16384
	ds_read_b64_tr_b16 v[154:155], v146 offset:8192
	ds_read_b64_tr_b16 v[158:159], v146 offset:16384
	ds_read_b64_tr_b16 v[162:163], v146 offset:24576
	s_waitcnt lgkmcnt(6)
; #define LAS __attribute__((address_space(3)))
; __device__ __forceinline__ s16x4 tr_read(const LAS unsigned char* p) { return __builtin_amdgcn_ds_read_tr16_b64_v4i16((LAS s16x4*)p); }
; __device__ __forceinline__ bf16x8 cat8(s16x4 a, s16x4 b) { return (bf16x8){a[0], a[1], a[2], a[3], b[0], b[1], b[2], b[3]}; }
; __device__ __forceinline__ f32x4 mfma16(bf16x8 a, bf16x8 b, f32x4 c) { return __builtin_amdgcn_mfma_f32_16x16x32_bf16(a, b, c, 0, 0, 0); }
; __device__ __forceinline__ void ret_phase(const Params& P, LAS unsigned char* lds, int tid, int lane, int wave, int bid, int G) {
;     ...
; #pragma unroll
;         for (int ks = 0; ks < 4; ++ks) {
;             const bf16x8 pa = *(const LAS bf16x8*)(Pt + off256(w16 + l15, 4 * ks + g));
;             const unsigned r0 = 32 * ks + 8 * g + q4, r1 = r0 + 4;
; #pragma unroll
;             for (int t = 0; t < 8; ++t) { const unsigned ch = 2 * t + (p >> 1);
;                 const bf16x8 vb = cat8(tr_read(Vt + off256(r0, ch) + 8 * (p & 1)), tr_read(Vt + off256(r1, ch) + 8 * (p & 1)));
;                 o[t] = mfma16(pa, vb, o[t]); }
;         }
	v_mfma_f32_16x16x32_bf16 v[74:77], v[62:65], v[102:105], v[74:77]
	v_bitop3_b32 v102, v151, v171, v119 bitop3:0x36
	v_lshl_add_u32 v102, v102, 4, v156
	ds_read_b64_tr_b16 v[146:147], v102
	v_bitop3_b32 v102, v141, v200, v119 bitop3:0x36
	v_bitop3_b32 v104, v151, v200, v119 bitop3:0x36
	v_lshl_add_u32 v190, v102, 4, v150
	v_lshl_add_u32 v104, v104, 4, v156
	ds_read_b64_tr_b16 v[102:103], v190
	ds_read_b64_tr_b16 v[164:165], v190 offset:8192
	ds_read_b64_tr_b16 v[168:169], v160 offset:24576
	s_waitcnt lgkmcnt(3)
	v_mfma_f32_16x16x32_bf16 v[82:85], v[62:65], v[144:147], v[82:85]
	ds_read_b64_tr_b16 v[104:105], v104
	v_bitop3_b32 v144, v141, v201, v119 bitop3:0x36
	v_lshl_add_u32 v160, v144, 4, v150
	v_bitop3_b32 v144, v151, v201, v119 bitop3:0x36
	v_lshl_add_u32 v144, v144, 4, v156
	ds_read_b64_tr_b16 v[146:147], v144
	ds_read_b64_tr_b16 v[144:145], v160
	ds_read_b64_tr_b16 v[172:173], v190 offset:24576
	s_waitcnt lgkmcnt(3)
	v_mfma_f32_16x16x32_bf16 v[78:81], v[62:65], v[102:105], v[78:81]
	v_bitop3_b32 v104, v141, v202, v119 bitop3:0x36
	v_lshl_add_u32 v104, v104, 4, v150
	v_bitop3_b32 v105, v151, v202, v119 bitop3:0x36
	ds_read_b64_tr_b16 v[102:103], v160 offset:24576
	s_waitcnt lgkmcnt(2)
	v_mfma_f32_16x16x32_bf16 v[90:93], v[62:65], v[144:147], v[90:93]
	ds_read_b64_tr_b16 v[144:145], v104
	v_lshl_add_u32 v105, v105, 4, v156
	v_bitop3_b32 v146, v141, v203, v119 bitop3:0x36
	v_lshl_add_u32 v161, v146, 4, v150
	ds_read_b64_tr_b16 v[146:147], v105
	ds_read_b64_tr_b16 v[174:175], v161
	ds_read_b64_tr_b16 v[178:179], v161 offset:8192
	ds_read_b64_tr_b16 v[182:183], v161 offset:16384
	ds_read_b64_tr_b16 v[184:185], v104 offset:8192
	ds_read_b64_tr_b16 v[188:189], v104 offset:16384
	ds_read_b64_tr_b16 v[192:193], v104 offset:24576
	v_bitop3_b32 v104, v151, v203, v119 bitop3:0x36
	v_lshl_add_u32 v104, v104, 4, v156
	ds_read_b64_tr_b16 v[176:177], v104
	v_bitop3_b32 v105, v151, v204, v119 bitop3:0x36
	v_bitop3_b32 v104, v141, v204, v119 bitop3:0x36
	v_lshl_add_u32 v105, v105, 4, v156
	s_waitcnt lgkmcnt(7)
	v_mfma_f32_16x16x32_bf16 v[86:89], v[62:65], v[144:147], v[86:89]
	v_lshl_add_u32 v104, v104, 4, v150
	ds_read_b64_tr_b16 v[146:147], v105
	ds_read_b64_tr_b16 v[144:145], v104
	ds_read_b64_tr_b16 v[194:195], v104 offset:8192
	ds_read_b64_tr_b16 v[198:199], v161 offset:24576
	v_pk_mul_f32 v[52:53], v[124:125], v[52:53]
	v_pk_mul_f32 v[50:51], v[122:123], v[50:51]
	s_waitcnt lgkmcnt(4)
	v_mfma_f32_16x16x32_bf16 v[94:97], v[62:65], v[174:177], v[94:97]
	ds_read_b64_tr_b16 v[122:123], v104 offset:24576
	v_add_u32_e32 v105, 36, v137
	v_bfe_u32 v124, v105, 2, 2
	s_waitcnt lgkmcnt(3)
	v_mfma_f32_16x16x32_bf16 v[50:53], v[62:65], v[144:147], v[50:53]
	v_add_u32_e32 v62, 4, v118
	v_bitop3_b32 v62, v136, v62, v138 bitop3:0x36
	v_lshl_add_u32 v62, v62, 4, v139
	ds_read_b128 v[62:65], v62
	v_lshl_add_u32 v105, v105, 8, v140
	v_bitop3_b32 v125, v124, v135, v119 bitop3:0x36
	v_lshl_add_u32 v125, v125, 4, v105
	ds_read_b64_tr_b16 v[146:147], v125
	ds_read_b64_tr_b16 v[144:145], v157 offset:8192
	ds_read_b64_tr_b16 v[174:175], v157 offset:16384
	v_bitop3_b32 v125, v124, v170, v119 bitop3:0x36
	v_lshl_add_u32 v125, v125, 4, v105
	ds_read_b64_tr_b16 v[156:157], v125
	v_bitop3_b32 v125, v124, v171, v119 bitop3:0x36
	s_waitcnt lgkmcnt(2)
	v_mfma_f32_16x16x32_bf16 v[98:101], v[62:65], v[144:147], v[98:101]
	v_lshl_add_u32 v125, v125, 4, v105
	v_bitop3_b32 v141, v124, v200, v119 bitop3:0x36
	v_bitop3_b32 v144, v124, v201, v119 bitop3:0x36
	v_lshl_add_u32 v141, v141, 4, v105
	v_lshl_add_u32 v144, v144, 4, v105
	ds_read_b64_tr_b16 v[150:151], v125
	ds_read_b64_tr_b16 v[166:167], v141
	ds_read_b64_tr_b16 v[146:147], v144
	v_bitop3_b32 v125, v124, v202, v119 bitop3:0x36
	v_lshl_add_u32 v125, v125, 4, v105
	s_waitcnt lgkmcnt(2)
	v_mfma_f32_16x16x32_bf16 v[82:85], v[62:65], v[148:151], v[82:85]
	ds_read_b64_tr_b16 v[144:145], v160 offset:8192
	ds_read_b64_tr_b16 v[148:149], v160 offset:16384
	ds_read_b64_tr_b16 v[186:187], v125
	v_bitop3_b32 v125, v124, v203, v119 bitop3:0x36
	v_lshl_add_u32 v125, v125, 4, v105
	v_bitop3_b32 v124, v124, v204, v119 bitop3:0x36
	v_lshl_add_u32 v105, v124, 4, v105
	ds_read_b64_tr_b16 v[180:181], v125
	ds_read_b64_tr_b16 v[196:197], v105
	v_add_u32_e32 v105, 0x44, v137
	v_mfma_f32_16x16x32_bf16 v[74:77], v[62:65], v[154:157], v[74:77]
	v_bfe_u32 v124, v105, 2, 2
	v_lshl_add_u32 v105, v105, 8, v140
	v_bitop3_b32 v125, v124, v135, v119 bitop3:0x36
	s_waitcnt lgkmcnt(6)
	v_mfma_f32_16x16x32_bf16 v[78:81], v[62:65], v[164:167], v[78:81]
	v_lshl_add_u32 v125, v125, 4, v105
	ds_read_b64_tr_b16 v[176:177], v125
	v_bitop3_b32 v125, v124, v170, v119 bitop3:0x36
	s_waitcnt lgkmcnt(5)
	v_mfma_f32_16x16x32_bf16 v[90:93], v[62:65], v[144:147], v[90:93]
	v_lshl_add_u32 v125, v125, 4, v105
	ds_read_b64_tr_b16 v[160:161], v125
	v_bitop3_b32 v125, v124, v171, v119 bitop3:0x36
	s_waitcnt lgkmcnt(4)
	v_mfma_f32_16x16x32_bf16 v[86:89], v[62:65], v[184:187], v[86:89]
	v_bitop3_b32 v144, v124, v201, v119 bitop3:0x36
	v_lshl_add_u32 v125, v125, 4, v105
	v_bitop3_b32 v141, v124, v200, v119 bitop3:0x36
	s_waitcnt lgkmcnt(3)
	v_mfma_f32_16x16x32_bf16 v[94:97], v[62:65], v[178:181], v[94:97]
	v_lshl_add_u32 v144, v144, 4, v105
	v_lshl_add_u32 v141, v141, 4, v105
	s_waitcnt lgkmcnt(2)
	v_mfma_f32_16x16x32_bf16 v[50:53], v[62:65], v[194:197], v[50:53]
	v_add_u32_e32 v62, 8, v118
	v_bitop3_b32 v62, v136, v62, v138 bitop3:0x36
	v_lshl_add_u32 v62, v62, 4, v139
	ds_read_b128 v[62:65], v62
	ds_read_b64_tr_b16 v[154:155], v125
	ds_read_b64_tr_b16 v[146:147], v141
	ds_read_b64_tr_b16 v[150:151], v144
	ds_read_b64_tr_b16 v[144:145], v190 offset:16384
	s_waitcnt lgkmcnt(0)
; #define LAS __attribute__((address_space(3)))
; __device__ __forceinline__ s16x4 tr_read(const LAS unsigned char* p) { return __builtin_amdgcn_ds_read_tr16_b64_v4i16((LAS s16x4*)p); }
; __device__ __forceinline__ bf16x8 cat8(s16x4 a, s16x4 b) { return (bf16x8){a[0], a[1], a[2], a[3], b[0], b[1], b[2], b[3]}; }
; __device__ __forceinline__ f32x4 mfma16(bf16x8 a, bf16x8 b, f32x4 c) { return __builtin_amdgcn_mfma_f32_16x16x32_bf16(a, b, c, 0, 0, 0); }
; #define OPQ_ALL() do { asm volatile("" : "+v"(g), "+v"(l15), "+v"(q4), "+v"(p)); } while (0)
; __device__ __forceinline__ void ret_phase(const Params& P, LAS unsigned char* lds, int tid, int lane, int wave, int bid, int G) {
;     ...
; #pragma unroll
;         for (int ks = 0; ks < 4; ++ks) {
;             const bf16x8 pa = *(const LAS bf16x8*)(Pt + off256(w16 + l15, 4 * ks + g));
;             const unsigned r0 = 32 * ks + 8 * g + q4, r1 = r0 + 4;
; #pragma unroll
;             for (int t = 0; t < 8; ++t) { const unsigned ch = 2 * t + (p >> 1);
;                 const bf16x8 vb = cat8(tr_read(Vt + off256(r0, ch) + 8 * (p & 1)), tr_read(Vt + off256(r1, ch) + 8 * (p & 1)));
;                 o[t] = mfma16(pa, vb, o[t]); }
;         }
;         OPQ_ALL();
;         float rs[4];
; #pragma unroll
;         for (int i = 0; i < 4; ++i) { float ss = 0.f;
; #pragma unroll
;             for (int t = 0; t < 8; ++t) ss += o[t][i] * o[t][i];
;             ss += __shfl_xor(ss, 1); ss += __shfl_xor(ss, 2); ss += __shfl_xor(ss, 4); ss += __shfl_xor(ss, 8);
;             rs[i] = rsqrtf(ss * (1.f / 128.f) + EPS); }
	v_mfma_f32_16x16x32_bf16 v[78:81], v[62:65], v[144:147], v[78:81]
	v_mfma_f32_16x16x32_bf16 v[146:149], v[62:65], v[148:151], v[90:93]
	s_nop 2
	v_bitop3_b32 v90, v124, v202, v119 bitop3:0x36
	v_lshl_add_u32 v90, v90, 4, v105
	ds_read_b64_tr_b16 v[190:191], v90
	v_bitop3_b32 v90, v124, v203, v119 bitop3:0x36
	v_bitop3_b32 v91, v124, v204, v119 bitop3:0x36
	v_lshl_add_u32 v90, v90, 4, v105
	v_lshl_add_u32 v91, v91, 4, v105
	v_mfma_f32_16x16x32_bf16 v[82:85], v[62:65], v[152:155], v[82:85]
	ds_read_b64_tr_b16 v[184:185], v90
	ds_read_b64_tr_b16 v[90:91], v91
	s_waitcnt lgkmcnt(2)
	v_mfma_f32_16x16x32_bf16 v[150:153], v[62:65], v[188:191], v[86:89]
	s_nop 2
	ds_read_b64_tr_b16 v[88:89], v104 offset:16384
	v_mfma_f32_16x16x32_bf16 v[98:101], v[62:65], v[174:177], v[98:101]
	v_mfma_f32_16x16x32_bf16 v[74:77], v[62:65], v[158:161], v[74:77]
	s_waitcnt lgkmcnt(2)
	v_mfma_f32_16x16x32_bf16 v[154:157], v[62:65], v[182:185], v[94:97]
	s_waitcnt lgkmcnt(0)
	v_mfma_f32_16x16x32_bf16 v[50:53], v[62:65], v[88:91], v[50:53]
	v_add_u32_e32 v62, 12, v118
	v_bitop3_b32 v62, v136, v62, v138 bitop3:0x36
	v_lshl_add_u32 v62, v62, 4, v139
	ds_read_b128 v[158:161], v62
	v_add_u32_e32 v62, 0x64, v137
	v_bfe_u32 v63, v62, 2, 2
	v_lshl_add_u32 v62, v62, 8, v140
	v_bitop3_b32 v64, v63, v135, v119 bitop3:0x36
	v_lshl_add_u32 v64, v64, 4, v62
	ds_read_b64_tr_b16 v[144:145], v64
	v_bitop3_b32 v64, v63, v170, v119 bitop3:0x36
	v_lshl_add_u32 v64, v64, 4, v62
	ds_read_b64_tr_b16 v[164:165], v64
	v_bitop3_b32 v64, v63, v171, v119 bitop3:0x36
	v_lshl_add_u32 v64, v64, 4, v62
	v_bitop3_b32 v65, v63, v200, v119 bitop3:0x36
	v_bitop3_b32 v86, v63, v201, v119 bitop3:0x36
	v_lshl_add_u32 v65, v65, 4, v62
	v_lshl_add_u32 v86, v86, 4, v62
	ds_read_b64_tr_b16 v[170:171], v64
	ds_read_b64_tr_b16 v[174:175], v65
	ds_read_b64_tr_b16 v[104:105], v86
	v_bitop3_b32 v64, v63, v202, v119 bitop3:0x36
	v_lshl_add_u32 v64, v64, 4, v62
	ds_read_b64_tr_b16 v[194:195], v64
	v_bitop3_b32 v64, v63, v203, v119 bitop3:0x36
	v_lshl_add_u32 v64, v64, 4, v62
	v_bitop3_b32 v63, v63, v204, v119 bitop3:0x36
	v_lshl_add_u32 v62, v63, 4, v62
	ds_read_b64_tr_b16 v[200:201], v64
	ds_read_b64_tr_b16 v[124:125], v62
	s_waitcnt lgkmcnt(7)
	v_mfma_f32_16x16x32_bf16 v[94:97], v[158:161], v[142:145], v[98:101]
	v_xor_b32_e32 v140, 2, v134
	s_waitcnt lgkmcnt(0)
	s_barrier
	s_waitcnt lgkmcnt(5)
	v_mfma_f32_16x16x32_bf16 v[86:89], v[158:161], v[168:171], v[82:85]
	v_and_b32_e32 v99, 64, v134
	v_xor_b32_e32 v98, 1, v134
	s_waitcnt lgkmcnt(4)
	v_mfma_f32_16x16x32_bf16 v[82:85], v[158:161], v[172:175], v[78:81]
	v_add_u32_e32 v119, 64, v99
	v_cmp_lt_i32_e32 vcc, v98, v119
	v_mfma_f32_16x16x32_bf16 v[90:93], v[158:161], v[162:165], v[74:77]
	s_nop 0
	v_cndmask_b32_e32 v98, v134, v98, vcc
	v_lshlrev_b32_e32 v135, 2, v98
	v_mov_b32_e32 v98, v86
	s_waitcnt lgkmcnt(3)
	v_mfma_f32_16x16x32_bf16 v[78:81], v[158:161], v[102:105], v[146:149]
	v_mov_b32_e32 v99, v82
	v_mov_b32_e32 v104, v87
	v_mov_b32_e32 v105, v83
	s_waitcnt lgkmcnt(2)
	v_mfma_f32_16x16x32_bf16 v[74:77], v[158:161], v[192:195], v[150:153]
	v_mul_f32_e64 v98, v98, v98
	v_mul_f32_e64 v99, v99, v99
	v_pk_mul_f32 v[104:105], v[104:105], v[104:105]
	v_mov_b32_e32 v100, v78
	s_waitcnt lgkmcnt(1)
	v_mfma_f32_16x16x32_bf16 v[62:65], v[158:161], v[198:201], v[154:157]
	v_mov_b32_e32 v138, v104
	s_nop 0
	v_mov_b32_e32 v101, v74
	v_mov_b32_e32 v139, v98
	s_waitcnt lgkmcnt(0)
	v_mfma_f32_16x16x32_bf16 v[50:53], v[158:161], v[122:125], v[50:53]
	v_mul_f32_e64 v122, v90, v90
	v_mul_f32_e64 v123, v91, v91
	v_mov_b32_e32 v124, v79
	v_pk_fma_f32 v[122:123], v[94:95], v[94:95], v[122:123]
	v_mov_b32_e32 v125, v75
	v_pk_mul_f32 v[100:101], v[100:101], v[100:101]
	v_pk_mul_f32 v[124:125], v[124:125], v[124:125]
	v_pk_add_f32 v[122:123], v[122:123], v[138:139] op_sel:[1,0] op_sel_hi:[0,1]
	v_mov_b32_e32 v98, v105
	v_mov_b32_e32 v102, v62
	v_mov_b32_e32 v103, v50
	v_mov_b32_e32 v136, v63
	v_mov_b32_e32 v137, v51
	v_pk_add_f32 v[98:99], v[122:123], v[98:99]
	v_mov_b32_e32 v104, v124
	v_mov_b32_e32 v105, v100
	v_pk_mul_f32 v[102:103], v[102:103], v[102:103]
	v_pk_mul_f32 v[136:137], v[136:137], v[136:137]
	v_pk_add_f32 v[98:99], v[98:99], v[104:105]
	v_mov_b32_e32 v100, v125
	v_pk_add_f32 v[98:99], v[98:99], v[100:101]
	v_mov_b32_e32 v100, v136
	v_mov_b32_e32 v101, v102
	v_pk_add_f32 v[98:99], v[98:99], v[100:101]
	v_mov_b32_e32 v102, v137
	v_pk_add_f32 v[98:99], v[98:99], v[102:103]
	ds_bpermute_b32 v101, v135, v99
	ds_bpermute_b32 v100, v135, v98
	v_cmp_lt_i32_e32 vcc, v140, v119
	v_mov_b32_e32 v122, v88
	v_mov_b32_e32 v123, v84
	v_cndmask_b32_e32 v102, v134, v140, vcc
	v_lshlrev_b32_e32 v146, 2, v102
	s_waitcnt lgkmcnt(0)
	v_pk_add_f32 v[98:99], v[98:99], v[100:101]
	ds_bpermute_b32 v101, v146, v99
	ds_bpermute_b32 v100, v146, v98
	v_xor_b32_e32 v102, 4, v134
	v_cmp_lt_i32_e32 vcc, v102, v119
	v_mov_b32_e32 v138, v89
	v_mov_b32_e32 v139, v85
	v_cndmask_b32_e32 v102, v134, v102, vcc
	v_lshlrev_b32_e32 v147, 2, v102
	s_waitcnt lgkmcnt(0)
	v_pk_add_f32 v[98:99], v[98:99], v[100:101]
	ds_bpermute_b32 v101, v147, v99
	ds_bpermute_b32 v100, v147, v98
	v_xor_b32_e32 v102, 8, v134
	v_cmp_lt_i32_e32 vcc, v102, v119
	v_pk_mul_f32 v[122:123], v[122:123], v[122:123]
	v_pk_mul_f32 v[138:139], v[138:139], v[138:139]
	s_waitcnt lgkmcnt(0)
; __device__ __forceinline__ unsigned cvt_pk_bf16(float lo, float hi) { unsigned r; asm volatile("v_cvt_pk_bf16_f32 %0, %1, %2" : "=v"(r) : "v"(lo), "v"(hi)); return r; }
; #define LAS __attribute__((address_space(3)))
; #define LBAR() asm volatile("s_waitcnt lgkmcnt(0)\n\ts_barrier" ::: "memory")
; __device__ __forceinline__ void ret_phase(const Params& P, LAS unsigned char* lds, int tid, int lane, int wave, int bid, int G) {
;     ...
;         for (int i = 0; i < 4; ++i) { float ss = 0.f;
; #pragma unroll
;             for (int t = 0; t < 8; ++t) ss += o[t][i] * o[t][i];
;             ss += __shfl_xor(ss, 1); ss += __shfl_xor(ss, 2); ss += __shfl_xor(ss, 4); ss += __shfl_xor(ss, 8);
;             rs[i] = rsqrtf(ss * (1.f / 128.f) + EPS); }
;         LBAR();
; #pragma unroll
;         for (int t = 0; t < 8; ++t) { const int dv = 16 * t + l15; const float gn = P.rgain[h * 128 + dv];
; #pragma unroll
;             for (int i = 0; i < 4; ++i) { const int n = w16 + 4 * g + i; const unsigned wv = cvt_pk_bf16(o[t][i] * rs[i] * gn, 0.f);
;                 *(LAS unsigned short*)(Pt + off256(n, dv >> 3) + 2 * (dv & 7)) = (unsigned short)(wv & 0xffffu); } }
	v_pk_add_f32 v[100:101], v[98:99], v[100:101]
	v_lshl_add_u32 v98, s57, 7, v1
	v_ashrrev_i32_e32 v99, 31, v98
	v_lshl_add_u64 v[98:99], v[98:99], 2, s[62:63]
	v_mov_b32_e32 v148, v205
	v_cndmask_b32_e32 v102, v134, v102, vcc
	v_lshlrev_b32_e32 v119, 2, v102
	v_pk_mul_f32 v[102:103], v[92:93], v[92:93]
	v_mov_b32_e32 v124, v80
	v_pk_fma_f32 v[102:103], v[96:97], v[96:97], v[102:103]
	v_mov_b32_e32 v125, v76
	v_mov_b32_e32 v140, v81
	v_mov_b32_e32 v141, v77
	v_mov_b32_e32 v144, v138
	v_mov_b32_e32 v145, v122
	v_pk_mul_f32 v[124:125], v[124:125], v[124:125]
	v_pk_mul_f32 v[140:141], v[140:141], v[140:141]
	v_pk_add_f32 v[102:103], v[102:103], v[144:145] op_sel:[1,0] op_sel_hi:[0,1]
	v_mov_b32_e32 v122, v139
	v_mov_b32_e32 v136, v64
	v_mov_b32_e32 v137, v52
	v_mov_b32_e32 v142, v65
	v_mov_b32_e32 v143, v53
	v_pk_add_f32 v[102:103], v[102:103], v[122:123]
	v_mov_b32_e32 v122, v140
	v_mov_b32_e32 v123, v124
	v_pk_mul_f32 v[136:137], v[136:137], v[136:137]
	v_pk_mul_f32 v[142:143], v[142:143], v[142:143]
	v_pk_add_f32 v[102:103], v[102:103], v[122:123]
	v_mov_b32_e32 v124, v141
	v_pk_add_f32 v[102:103], v[102:103], v[124:125]
	v_mov_b32_e32 v122, v142
	v_mov_b32_e32 v123, v136
	v_pk_add_f32 v[102:103], v[102:103], v[122:123]
	v_mov_b32_e32 v136, v143
	v_pk_add_f32 v[102:103], v[102:103], v[136:137]
	ds_bpermute_b32 v123, v135, v103
	ds_bpermute_b32 v122, v135, v102
	ds_bpermute_b32 v105, v119, v101
	ds_bpermute_b32 v104, v119, v100
	s_waitcnt lgkmcnt(2)
	v_pk_add_f32 v[102:103], v[102:103], v[122:123]
	ds_bpermute_b32 v123, v146, v103
	ds_bpermute_b32 v122, v146, v102
	s_waitcnt lgkmcnt(2)
	v_pk_add_f32 v[100:101], v[100:101], v[104:105]
	v_mov_b64_e32 v[104:105], s[24:25]
	v_pk_fma_f32 v[100:101], v[100:101], s[20:21], v[104:105] op_sel_hi:[1,0,0]
	s_waitcnt lgkmcnt(0)
	v_pk_add_f32 v[102:103], v[102:103], v[122:123]
	ds_bpermute_b32 v123, v147, v103
	ds_bpermute_b32 v122, v147, v102
	v_mul_f32_e32 v124, 0x4b800000, v101
	v_cmp_gt_f32_e32 vcc, s54, v101
	v_cmp_gt_f32_e64 s[0:1], s54, v100
	s_nop 0
	v_cndmask_b32_e32 v101, v101, v124, vcc
	v_rsq_f32_e32 v124, v101
	v_mul_f32_e32 v101, 0x4b800000, v100
	v_cndmask_b32_e64 v100, v100, v101, s[0:1]
	v_rsq_f32_e32 v125, v100
	s_waitcnt lgkmcnt(0)
	v_pk_add_f32 v[100:101], v[102:103], v[122:123]
	ds_bpermute_b32 v103, v119, v101
	ds_bpermute_b32 v102, v119, v100
	v_mul_f32_e32 v119, 0x45800000, v124
	v_cndmask_b32_e32 v119, v124, v119, vcc
	v_mul_f32_e32 v122, 0x45800000, v125
	v_mul_f32_e32 v94, v94, v119
	s_waitcnt lgkmcnt(0)
	v_pk_add_f32 v[100:101], v[100:101], v[102:103]
	v_mul_f32_e32 v90, v90, v119
	v_pk_fma_f32 v[100:101], v[100:101], s[20:21], v[104:105] op_sel_hi:[1,0,0]
	v_lshlrev_b32_e32 v105, 1, v1
	v_mul_f32_e32 v102, 0x4b800000, v101
	v_cmp_gt_f32_e32 vcc, s54, v101
	v_cmp_gt_f32_e64 s[4:5], s54, v100
	v_and_b32_e32 v105, 14, v105
	v_cndmask_b32_e32 v101, v101, v102, vcc
	v_mul_f32_e32 v102, 0x4b800000, v100
	v_rsq_f32_e32 v101, v101
	v_cndmask_b32_e64 v100, v100, v102, s[4:5]
	v_rsq_f32_e32 v100, v100
	v_cndmask_b32_e64 v102, v125, v122, s[0:1]
	v_mul_f32_e32 v103, 0x45800000, v101
	v_cndmask_b32_e32 v101, v101, v103, vcc
	v_mul_f32_e32 v103, 0x45800000, v100
	v_lshrrev_b32_e32 v122, 3, v1
	v_cndmask_b32_e64 v100, v100, v103, s[4:5]
	v_lshlrev_b32_e32 v103, 2, v118
	v_bitop3_b32 v124, v118, v122, 3 bitop3:0x6c
	s_waitcnt vmcnt(0)
	v_mul_f32_e32 v94, v94, v148
	v_add_lshl_u32 v123, v103, s46, 8
	v_lshl_add_u32 v124, v124, 4, s51
	v_and_b32_e32 v104, 3, v118
	v_cvt_pk_bf16_f32 v94, v94, v115
	v_add3_u32 v124, v124, v123, v105
	ds_write_b16 v124, v94
	v_mul_f32_e32 v94, v95, v102
	v_bitop3_b32 v95, v104, v122, 4 bitop3:0x36
	v_mul_f32_e32 v94, v148, v94
	v_lshl_add_u32 v95, v95, 4, s51
	v_cvt_pk_bf16_f32 v94, v94, v115
	v_add3_u32 v95, v95, v123, v105
	ds_write_b16 v95, v94 offset:256
	v_mul_f32_e32 v94, v96, v101
	v_bitop3_b32 v95, v104, v122, 8 bitop3:0x36
	v_mul_f32_e32 v94, v148, v94
	v_lshl_add_u32 v95, v95, 4, s51
	v_cvt_pk_bf16_f32 v94, v94, v115
	v_add3_u32 v95, v95, v123, v105
	ds_write_b16 v95, v94 offset:512
	v_mul_f32_e32 v94, v97, v100
	v_mul_f32_e32 v94, v148, v94
	v_cvt_pk_bf16_f32 v94, v94, v115
	v_mov_b32_e32 v95, v206
	v_bitop3_b32 v96, v104, v122, 12 bitop3:0x36
	v_lshl_add_u32 v96, v96, 4, s51
	v_add3_u32 v96, v96, v123, v105
	ds_write_b16 v96, v94 offset:768
	v_add_u32_e32 v94, 16, v1
	v_lshrrev_b32_e32 v94, 3, v94
	v_bitop3_b32 v96, v94, v118, 3 bitop3:0x78
	v_lshl_add_u32 v96, v96, 4, s51
	v_add3_u32 v96, v96, v123, v105
	v_mul_f32_e32 v86, v86, v119
	v_mul_f32_e32 v82, v82, v119
	v_mul_f32_e32 v78, v78, v119
	v_mul_f32_e32 v74, v74, v119
	v_mul_f32_e32 v62, v62, v119
	v_mul_f32_e32 v50, v50, v119
	s_waitcnt vmcnt(0)
	v_mul_f32_e32 v90, v90, v95
	v_cvt_pk_bf16_f32 v90, v90, v115
	ds_write_b16 v96, v90
	v_mul_f32_e32 v90, v91, v102
	v_bitop3_b32 v91, v104, v94, 4 bitop3:0x36
	v_mul_f32_e32 v90, v90, v95
	v_lshl_add_u32 v91, v91, 4, s51
	v_cvt_pk_bf16_f32 v90, v90, v115
	v_add3_u32 v91, v91, v123, v105
	ds_write_b16 v91, v90 offset:256
	v_mul_f32_e32 v90, v92, v101
	v_bitop3_b32 v91, v104, v94, 8 bitop3:0x36
	v_mul_f32_e32 v90, v90, v95
	v_lshl_add_u32 v91, v91, 4, s51
	v_cvt_pk_bf16_f32 v90, v90, v115
	v_add3_u32 v91, v91, v123, v105
	ds_write_b16 v91, v90 offset:512
	v_mul_f32_e32 v90, v93, v100
	v_mul_f32_e32 v90, v90, v95
	v_cvt_pk_bf16_f32 v90, v90, v115
	v_mov_b32_e32 v91, v207
	v_bitop3_b32 v92, v104, v94, 12 bitop3:0x36
	v_lshl_add_u32 v92, v92, 4, s51
	v_add3_u32 v92, v92, v123, v105
	ds_write_b16 v92, v90 offset:768
	v_add_u32_e32 v90, 32, v1
	v_lshrrev_b32_e32 v90, 3, v90
	v_bitop3_b32 v92, v90, v118, 3 bitop3:0x78
	v_lshl_add_u32 v92, v92, 4, s51
	v_add3_u32 v92, v92, v123, v105
	s_waitcnt vmcnt(0)
; __device__ __forceinline__ unsigned cvt_pk_bf16(float lo, float hi) { unsigned r; asm volatile("v_cvt_pk_bf16_f32 %0, %1, %2" : "=v"(r) : "v"(lo), "v"(hi)); return r; }
; #define LAS __attribute__((address_space(3)))
; __device__ __forceinline__ void ret_phase(const Params& P, LAS unsigned char* lds, int tid, int lane, int wave, int bid, int G) {
;     ...
;         for (int t = 0; t < 8; ++t) { const int dv = 16 * t + l15; const float gn = P.rgain[h * 128 + dv];
; #pragma unroll
;             for (int i = 0; i < 4; ++i) { const int n = w16 + 4 * g + i; const unsigned wv = cvt_pk_bf16(o[t][i] * rs[i] * gn, 0.f);
;                 *(LAS unsigned short*)(Pt + off256(n, dv >> 3) + 2 * (dv & 7)) = (unsigned short)(wv & 0xffffu); } }
	v_mul_f32_e32 v86, v86, v91
	v_cvt_pk_bf16_f32 v86, v86, v115
	ds_write_b16 v92, v86
	v_mul_f32_e32 v86, v87, v102
	v_bitop3_b32 v87, v104, v90, 4 bitop3:0x36
	v_mul_f32_e32 v86, v86, v91
	v_lshl_add_u32 v87, v87, 4, s51
	v_cvt_pk_bf16_f32 v86, v86, v115
	v_add3_u32 v87, v87, v123, v105
	ds_write_b16 v87, v86 offset:256
	v_mul_f32_e32 v86, v88, v101
	v_bitop3_b32 v87, v104, v90, 8 bitop3:0x36
	v_mul_f32_e32 v86, v86, v91
	v_lshl_add_u32 v87, v87, 4, s51
	v_cvt_pk_bf16_f32 v86, v86, v115
	v_add3_u32 v87, v87, v123, v105
	ds_write_b16 v87, v86 offset:512
	v_mul_f32_e32 v86, v89, v100
	v_mul_f32_e32 v86, v86, v91
	v_cvt_pk_bf16_f32 v86, v86, v115
	v_mov_b32_e32 v87, v208
	v_bitop3_b32 v88, v104, v90, 12 bitop3:0x36
	v_lshl_add_u32 v88, v88, 4, s51
	v_add3_u32 v88, v88, v123, v105
	ds_write_b16 v88, v86 offset:768
	v_add_u32_e32 v86, 48, v1
	v_lshrrev_b32_e32 v86, 3, v86
	v_bitop3_b32 v88, v86, v118, 3 bitop3:0x78
	v_lshl_add_u32 v88, v88, 4, s51
	v_add3_u32 v88, v88, v123, v105
	s_waitcnt vmcnt(0)
	v_mul_f32_e32 v82, v82, v87
	v_cvt_pk_bf16_f32 v82, v82, v115
	ds_write_b16 v88, v82
	v_mul_f32_e32 v82, v83, v102
	v_bitop3_b32 v83, v104, v86, 4 bitop3:0x36
	v_mul_f32_e32 v82, v82, v87
	v_lshl_add_u32 v83, v83, 4, s51
	v_cvt_pk_bf16_f32 v82, v82, v115
	v_add3_u32 v83, v83, v123, v105
	ds_write_b16 v83, v82 offset:256
	v_mul_f32_e32 v82, v84, v101
	v_bitop3_b32 v83, v104, v86, 8 bitop3:0x36
	v_mul_f32_e32 v82, v82, v87
	v_lshl_add_u32 v83, v83, 4, s51
	v_cvt_pk_bf16_f32 v82, v82, v115
	v_add3_u32 v83, v83, v123, v105
	ds_write_b16 v83, v82 offset:512
	v_mul_f32_e32 v82, v85, v100
	v_mul_f32_e32 v82, v82, v87
	v_cvt_pk_bf16_f32 v82, v82, v115
	v_mov_b32_e32 v83, v209
	v_bitop3_b32 v84, v104, v86, 12 bitop3:0x36
	v_lshl_add_u32 v84, v84, 4, s51
	v_add3_u32 v84, v84, v123, v105
	ds_write_b16 v84, v82 offset:768
	v_add_u32_e32 v82, 64, v1
	v_lshrrev_b32_e32 v82, 3, v82
	v_bitop3_b32 v84, v82, v118, 3 bitop3:0x78
	v_lshl_add_u32 v84, v84, 4, s51
	v_add3_u32 v84, v84, v123, v105
	s_waitcnt vmcnt(0)
	v_mul_f32_e32 v78, v78, v83
	v_cvt_pk_bf16_f32 v78, v78, v115
	ds_write_b16 v84, v78
	v_mul_f32_e32 v78, v79, v102
	v_bitop3_b32 v79, v104, v82, 4 bitop3:0x36
	v_mul_f32_e32 v78, v78, v83
	v_lshl_add_u32 v79, v79, 4, s51
	v_cvt_pk_bf16_f32 v78, v78, v115
	v_add3_u32 v79, v79, v123, v105
	ds_write_b16 v79, v78 offset:256
	v_mul_f32_e32 v78, v80, v101
	v_bitop3_b32 v79, v104, v82, 8 bitop3:0x36
	v_mul_f32_e32 v78, v78, v83
	v_lshl_add_u32 v79, v79, 4, s51
	v_cvt_pk_bf16_f32 v78, v78, v115
	v_add3_u32 v79, v79, v123, v105
	ds_write_b16 v79, v78 offset:512
	v_mul_f32_e32 v78, v81, v100
	v_mul_f32_e32 v78, v78, v83
	v_cvt_pk_bf16_f32 v78, v78, v115
	v_mov_b32_e32 v79, v210
	v_bitop3_b32 v80, v104, v82, 12 bitop3:0x36
	v_lshl_add_u32 v80, v80, 4, s51
	v_add3_u32 v80, v80, v123, v105
	ds_write_b16 v80, v78 offset:768
	v_add_u32_e32 v78, 0x50, v1
	v_lshrrev_b32_e32 v78, 3, v78
	v_bitop3_b32 v80, v78, v118, 3 bitop3:0x78
	v_lshl_add_u32 v80, v80, 4, s51
	v_add3_u32 v80, v80, v123, v105
	s_waitcnt vmcnt(0)
	v_mul_f32_e32 v74, v74, v79
	v_cvt_pk_bf16_f32 v74, v74, v115
	ds_write_b16 v80, v74
	v_mul_f32_e32 v74, v75, v102
	v_bitop3_b32 v75, v104, v78, 4 bitop3:0x36
	v_mul_f32_e32 v74, v74, v79
	v_lshl_add_u32 v75, v75, 4, s51
	v_cvt_pk_bf16_f32 v74, v74, v115
	v_add3_u32 v75, v75, v123, v105
	ds_write_b16 v75, v74 offset:256
	v_mul_f32_e32 v74, v76, v101
	v_bitop3_b32 v75, v104, v78, 8 bitop3:0x36
	v_mul_f32_e32 v74, v74, v79
	v_lshl_add_u32 v75, v75, 4, s51
	v_cvt_pk_bf16_f32 v74, v74, v115
	v_add3_u32 v75, v75, v123, v105
	ds_write_b16 v75, v74 offset:512
	v_mul_f32_e32 v74, v77, v100
	v_mul_f32_e32 v74, v74, v79
	v_cvt_pk_bf16_f32 v74, v74, v115
	v_mov_b32_e32 v75, v211
	v_bitop3_b32 v76, v104, v78, 12 bitop3:0x36
	v_lshl_add_u32 v76, v76, 4, s51
	v_add3_u32 v76, v76, v123, v105
	ds_write_b16 v76, v74 offset:768
	v_add_u32_e32 v74, 0x60, v1
	v_lshrrev_b32_e32 v74, 3, v74
	v_bitop3_b32 v76, v74, v118, 3 bitop3:0x78
	v_lshl_add_u32 v76, v76, 4, s51
	v_add3_u32 v76, v76, v123, v105
	v_and_b32_e32 v78, 12, v103
	s_waitcnt vmcnt(0)
	v_mul_f32_e32 v62, v62, v75
	v_cvt_pk_bf16_f32 v62, v62, v115
	ds_write_b16 v76, v62
	v_mul_f32_e32 v62, v63, v102
	v_bitop3_b32 v63, v104, v74, 4 bitop3:0x36
	v_mul_f32_e32 v62, v62, v75
	v_lshl_add_u32 v63, v63, 4, s51
	v_cvt_pk_bf16_f32 v62, v62, v115
	v_add3_u32 v63, v63, v123, v105
	ds_write_b16 v63, v62 offset:256
	v_mul_f32_e32 v62, v64, v101
	v_bitop3_b32 v63, v104, v74, 8 bitop3:0x36
	v_mul_f32_e32 v62, v62, v75
	v_lshl_add_u32 v63, v63, 4, s51
	v_cvt_pk_bf16_f32 v62, v62, v115
	v_add3_u32 v63, v63, v123, v105
	ds_write_b16 v63, v62 offset:512
	v_mul_f32_e32 v62, v65, v100
	v_mul_f32_e32 v62, v62, v75
	v_cvt_pk_bf16_f32 v62, v62, v115
	v_mov_b32_e32 v63, v212
	v_bitop3_b32 v64, v104, v74, 12 bitop3:0x36
	v_lshl_add_u32 v64, v64, 4, s51
	v_add3_u32 v64, v64, v123, v105
	ds_write_b16 v64, v62 offset:768
	v_add_u32_e32 v62, 0x70, v1
	v_lshrrev_b32_e32 v62, 3, v62
	v_bitop3_b32 v64, v62, v118, 3 bitop3:0x78
	v_lshl_add_u32 v64, v64, 4, s51
	v_add3_u32 v64, v64, v123, v105
	v_add_u32_e32 v74, s46, v118
	v_ashrrev_i32_e32 v75, 31, v74
	v_add_u32_e32 v76, 4, v74
	v_ashrrev_i32_e32 v77, 31, v76
	s_waitcnt vmcnt(0)
	v_mul_f32_e32 v50, v50, v63
	v_cvt_pk_bf16_f32 v50, v50, v115
	ds_write_b16 v64, v50
	v_mul_f32_e32 v50, v51, v102
	v_bitop3_b32 v51, v104, v62, 4 bitop3:0x36
	v_lshl_add_u32 v51, v51, 4, s51
	v_mul_f32_e32 v50, v50, v63
	v_add3_u32 v51, v51, v123, v105
	v_cvt_pk_bf16_f32 v50, v50, v115
	ds_write_b16 v51, v50 offset:256
	v_bitop3_b32 v51, v104, v62, 8 bitop3:0x36
	v_mul_f32_e32 v50, v52, v101
	v_lshl_add_u32 v51, v51, 4, s51
	v_mul_f32_e32 v50, v50, v63
	v_add3_u32 v51, v51, v123, v105
	v_cvt_pk_bf16_f32 v50, v50, v115
	ds_write_b16 v51, v50 offset:512
	v_bitop3_b32 v51, v104, v62, 12 bitop3:0x36
	v_mul_f32_e32 v50, v53, v100
	v_lshl_add_u32 v51, v51, 4, s51
	v_mul_f32_e32 v50, v50, v63
	v_add3_u32 v51, v51, v123, v105
	v_cvt_pk_bf16_f32 v50, v50, v115
	ds_write_b16 v51, v50 offset:768
	v_bfe_u32 v51, v118, 2, 2
	v_bitop3_b32 v51, v51, v1, v78 bitop3:0x36
	v_lshlrev_b32_e32 v50, 8, v74
	v_lshlrev_b32_e32 v51, 4, v51
	s_waitcnt lgkmcnt(0)
	s_barrier
; __device__ __forceinline__ unsigned cvt_pk_bf16(float lo, float hi) { unsigned r; asm volatile("v_cvt_pk_bf16_f32 %0, %1, %2" : "=v"(r) : "v"(lo), "v"(hi)); return r; }
; #define LAS __attribute__((address_space(3)))
; __device__ __forceinline__ float bf_lo(unsigned u) { return __uint_as_float(u << 16); }
; __device__ __forceinline__ float bf_hi(unsigned u) { return __uint_as_float(u & 0xffff0000u); }
; #define LBAR() asm volatile("s_waitcnt lgkmcnt(0)\n\ts_barrier" ::: "memory")
; __device__ __forceinline__ void ret_phase(const Params& P, LAS unsigned char* lds, int tid, int lane, int wave, int bid, int G) {
;     ...
; #pragma unroll
;         for (int it = 0; it < 4; ++it) { const int row = w16 + 4 * it + g, ch = l15;
;             const u32x4 ov = *(const LAS u32x4*)(Pt + off256(row, ch));
;             const u32x4 gv = grv[it];
;             u32x4 w; w.x = cvt_pk_bf16(bf_lo(ov.x) * bf_lo(gv.x), bf_hi(ov.x) * bf_hi(gv.x)); w.y = cvt_pk_bf16(bf_lo(ov.y) * bf_lo(gv.y), bf_hi(ov.y) * bf_hi(gv.y));
;             w.z = cvt_pk_bf16(bf_lo(ov.z) * bf_lo(gv.z), bf_hi(ov.z) * bf_hi(gv.z)); w.w = cvt_pk_bf16(bf_lo(ov.w) * bf_lo(gv.w), bf_hi(ov.w) * bf_hi(gv.w));
;             *(u32x4*)(MIX + (tokc + row) * DM + 512 + h * 128 + 8 * ch) = w; }
;         LBAR();
	v_add3_u32 v50, s51, v51, v50
	ds_read_b128 v[50:53], v50
	v_lshlrev_b32_e32 v64, 16, v70
	v_lshlrev_b32_e32 v62, 3, v1
	v_ashrrev_i32_e32 v63, 31, v62
	s_waitcnt lgkmcnt(0)
	v_lshlrev_b32_e32 v65, 16, v50
	v_mul_f32_e32 v64, v65, v64
	v_and_b32_e32 v50, 0xffff0000, v50
	v_and_b32_e32 v65, 0xffff0000, v70
	v_mul_f32_e32 v50, v50, v65
	v_cvt_pk_bf16_f32 v50, v64, v50
	v_lshlrev_b32_e32 v64, 16, v71
	v_lshlrev_b32_e32 v65, 16, v51
	v_mul_f32_e32 v64, v65, v64
	v_and_b32_e32 v51, 0xffff0000, v51
	v_and_b32_e32 v65, 0xffff0000, v71
	v_mul_f32_e32 v51, v51, v65
	v_cvt_pk_bf16_f32 v51, v64, v51
	v_lshlrev_b32_e32 v64, 16, v72
	v_lshlrev_b32_e32 v65, 16, v52
	v_mul_f32_e32 v64, v65, v64
	v_and_b32_e32 v52, 0xffff0000, v52
	v_and_b32_e32 v65, 0xffff0000, v72
	v_mul_f32_e32 v52, v52, v65
	v_cvt_pk_bf16_f32 v52, v64, v52
	v_lshlrev_b32_e32 v64, 16, v73
	v_lshlrev_b32_e32 v65, 16, v53
	v_mul_f32_e32 v64, v65, v64
	v_and_b32_e32 v53, 0xffff0000, v53
	v_and_b32_e32 v65, 0xffff0000, v73
	v_mul_f32_e32 v53, v53, v65
	v_cvt_pk_bf16_f32 v53, v64, v53
	v_lshl_add_u64 v[64:65], s[40:41], 0, v[74:75]
	v_lshlrev_b64 v[70:71], 1, v[62:63]
	v_bfe_u32 v63, v76, 2, 2
	v_lshlrev_b64 v[64:65], 11, v[64:65]
	v_bitop3_b32 v63, v63, v1, v78 bitop3:0x36
	v_lshl_add_u64 v[64:65], s[22:23], 0, v[64:65]
	v_lshlrev_b32_e32 v62, 8, v76
	v_lshlrev_b32_e32 v63, 4, v63
	v_lshl_add_u64 v[64:65], v[64:65], 0, s[18:19]
	v_add3_u32 v62, s51, v63, v62
	v_lshl_add_u64 v[72:73], v[64:65], 0, v[70:71]
	ds_read_b128 v[62:65], v62
	v_add_co_u32_e32 v72, vcc, s55, v72
	s_nop 1
	v_addc_co_u32_e32 v73, vcc, 0, v73, vcc
	global_store_dwordx4 v[72:73], v[50:53], off offset:1024
	s_nop 1
	v_lshlrev_b32_e32 v50, 16, v66
	s_waitcnt lgkmcnt(0)
	v_lshlrev_b32_e32 v51, 16, v62
	v_mul_f32_e32 v50, v51, v50
	v_and_b32_e32 v51, 0xffff0000, v62
	v_and_b32_e32 v52, 0xffff0000, v66
	v_mul_f32_e32 v51, v51, v52
	v_cvt_pk_bf16_f32 v50, v50, v51
	v_lshlrev_b32_e32 v51, 16, v67
	v_lshlrev_b32_e32 v52, 16, v63
	v_mul_f32_e32 v51, v52, v51
	v_and_b32_e32 v52, 0xffff0000, v63
	v_and_b32_e32 v53, 0xffff0000, v67
	v_mul_f32_e32 v52, v52, v53
	v_cvt_pk_bf16_f32 v51, v51, v52
	v_lshlrev_b32_e32 v52, 16, v68
	v_lshlrev_b32_e32 v53, 16, v64
	v_mul_f32_e32 v52, v53, v52
	v_and_b32_e32 v53, 0xffff0000, v64
	v_and_b32_e32 v62, 0xffff0000, v68
	v_mul_f32_e32 v53, v53, v62
	v_cvt_pk_bf16_f32 v52, v52, v53
	v_lshlrev_b32_e32 v53, 16, v69
	v_lshlrev_b32_e32 v62, 16, v65
	v_mul_f32_e32 v53, v62, v53
	v_and_b32_e32 v62, 0xffff0000, v65
	v_and_b32_e32 v63, 0xffff0000, v69
	v_mul_f32_e32 v62, v62, v63
	v_cvt_pk_bf16_f32 v53, v53, v62
	v_lshl_add_u64 v[62:63], s[40:41], 0, v[76:77]
	v_lshlrev_b64 v[62:63], 11, v[62:63]
	v_lshl_add_u64 v[62:63], s[22:23], 0, v[62:63]
	v_lshl_add_u64 v[62:63], v[62:63], 0, s[18:19]
	v_add_u32_e32 v68, 8, v74
	v_lshl_add_u64 v[66:67], v[62:63], 0, v[70:71]
	v_bfe_u32 v63, v68, 2, 2
	v_bitop3_b32 v63, v63, v1, v78 bitop3:0x36
	v_lshlrev_b32_e32 v62, 8, v68
	v_lshlrev_b32_e32 v63, 4, v63
	v_add3_u32 v62, s51, v63, v62
	ds_read_b128 v[62:65], v62
	v_add_co_u32_e32 v66, vcc, s55, v66
	v_ashrrev_i32_e32 v69, 31, v68
	s_nop 0
	v_addc_co_u32_e32 v67, vcc, 0, v67, vcc
	global_store_dwordx4 v[66:67], v[50:53], off offset:1024
	s_nop 1
	v_lshlrev_b32_e32 v50, 16, v58
	s_waitcnt lgkmcnt(0)
	v_lshlrev_b32_e32 v51, 16, v62
	v_mul_f32_e32 v50, v51, v50
	v_and_b32_e32 v51, 0xffff0000, v62
	v_and_b32_e32 v52, 0xffff0000, v58
	v_mul_f32_e32 v51, v51, v52
	v_cvt_pk_bf16_f32 v50, v50, v51
	v_lshlrev_b32_e32 v51, 16, v59
	v_lshlrev_b32_e32 v52, 16, v63
	v_mul_f32_e32 v51, v52, v51
	v_and_b32_e32 v52, 0xffff0000, v63
	v_and_b32_e32 v53, 0xffff0000, v59
	v_mul_f32_e32 v52, v52, v53
	v_cvt_pk_bf16_f32 v51, v51, v52
	v_lshlrev_b32_e32 v52, 16, v60
	v_lshlrev_b32_e32 v53, 16, v64
	v_mul_f32_e32 v52, v53, v52
	v_and_b32_e32 v53, 0xffff0000, v64
	v_and_b32_e32 v58, 0xffff0000, v60
	v_mul_f32_e32 v53, v53, v58
	v_cvt_pk_bf16_f32 v52, v52, v53
	v_lshlrev_b32_e32 v53, 16, v61
	v_lshlrev_b32_e32 v58, 16, v65
	v_mul_f32_e32 v53, v58, v53
	v_and_b32_e32 v58, 0xffff0000, v65
	v_and_b32_e32 v59, 0xffff0000, v61
	v_mul_f32_e32 v58, v58, v59
	v_cvt_pk_bf16_f32 v53, v53, v58
	v_lshl_add_u64 v[58:59], s[40:41], 0, v[68:69]
	v_lshlrev_b64 v[58:59], 11, v[58:59]
	v_lshl_add_u64 v[58:59], s[22:23], 0, v[58:59]
	v_lshl_add_u64 v[58:59], v[58:59], 0, s[18:19]
	v_add_u32_e32 v64, 12, v74
	v_lshl_add_u64 v[62:63], v[58:59], 0, v[70:71]
	v_bfe_u32 v59, v64, 2, 2
	v_bitop3_b32 v59, v59, v1, v78 bitop3:0x36
	v_lshlrev_b32_e32 v58, 8, v64
	v_lshlrev_b32_e32 v59, 4, v59
	v_add3_u32 v58, s51, v59, v58
	ds_read_b128 v[58:61], v58
	v_add_co_u32_e32 v62, vcc, s55, v62
	v_ashrrev_i32_e32 v65, 31, v64
	s_nop 0
	v_addc_co_u32_e32 v63, vcc, 0, v63, vcc
	global_store_dwordx4 v[62:63], v[50:53], off offset:1024
	s_nop 1
	v_lshlrev_b32_e32 v50, 16, v54
	s_waitcnt lgkmcnt(0)
	v_lshlrev_b32_e32 v51, 16, v58
	v_mul_f32_e32 v50, v51, v50
	v_and_b32_e32 v51, 0xffff0000, v58
	v_and_b32_e32 v52, 0xffff0000, v54
	v_mul_f32_e32 v51, v51, v52
	v_cvt_pk_bf16_f32 v50, v50, v51
	v_lshlrev_b32_e32 v51, 16, v55
	v_lshlrev_b32_e32 v52, 16, v59
	v_mul_f32_e32 v51, v52, v51
	v_and_b32_e32 v52, 0xffff0000, v59
	v_and_b32_e32 v53, 0xffff0000, v55
	v_mul_f32_e32 v52, v52, v53
	v_cvt_pk_bf16_f32 v51, v51, v52
	v_lshlrev_b32_e32 v52, 16, v56
	v_lshlrev_b32_e32 v53, 16, v60
	v_mul_f32_e32 v52, v53, v52
	v_and_b32_e32 v53, 0xffff0000, v60
	v_and_b32_e32 v54, 0xffff0000, v56
	v_mul_f32_e32 v53, v53, v54
	v_cvt_pk_bf16_f32 v52, v52, v53
	v_lshlrev_b32_e32 v53, 16, v57
	v_lshlrev_b32_e32 v54, 16, v61
	v_mul_f32_e32 v53, v54, v53
	v_and_b32_e32 v54, 0xffff0000, v61
	v_and_b32_e32 v55, 0xffff0000, v57
	v_mul_f32_e32 v54, v54, v55
	v_cvt_pk_bf16_f32 v53, v53, v54
	v_lshl_add_u64 v[54:55], s[40:41], 0, v[64:65]
	v_lshlrev_b64 v[54:55], 11, v[54:55]
	v_lshl_add_u64 v[54:55], s[22:23], 0, v[54:55]
	v_lshl_add_u64 v[54:55], v[54:55], 0, s[18:19]
	v_lshl_add_u64 v[54:55], v[54:55], 0, v[70:71]
	v_add_co_u32_e32 v54, vcc, 0x2000000, v54
	s_nop 1
	v_addc_co_u32_e32 v55, vcc, 0, v55, vcc
	global_store_dwordx4 v[54:55], v[50:53], off offset:1024
	s_waitcnt lgkmcnt(0)
	s_barrier
	s_andn2_b64 vcc, exec, s[42:43]
	s_cbranch_vccz .LBB0_393
; #define LAS __attribute__((address_space(3)))
; __device__ __forceinline__ f32x4 mfma16(bf16x8 a, bf16x8 b, f32x4 c) { return __builtin_amdgcn_mfma_f32_16x16x32_bf16(a, b, c, 0, 0, 0); }
; #define LBAR() asm volatile("s_waitcnt lgkmcnt(0)\n\ts_barrier" ::: "memory")
; #define OPQ_ALL() do { asm volatile("" : "+v"(g), "+v"(l15), "+v"(q4), "+v"(p)); } while (0)
; __device__ __forceinline__ void ret_phase(const Params& P, LAS unsigned char* lds, int tid, int lane, int wave, int bid, int G) {
;     ...
;         const int gc = u >> 2, h = u & 3; const size_t tokc = (size_t)gc * 128;
;         const float lgf2 = -__expf(P.dec_f[h]) * LOG2E, lgb2 = -__expf(P.dec_b[h]) * LOG2E;
; #pragma unroll
;         for (int i = 0; i < 4; ++i) { const int idx = tid + 512 * i; const unsigned d = off256(idx >> 4, idx & 15);
;             *(LAS u32x4*)(Qt + d) = rq[i]; *(LAS u32x4*)(Kt + d) = rk[i]; *(LAS u32x4*)(Vt + d) = rv[i]; }
;         LBAR();
;         const bf16_t* Sf = ST + ((size_t)(gc * 4 + h) * 2 + 0) * 16384; const bf16_t* Sb = Sf + 16384;
;         u32x4 rsf[2], rsb[2];
; #pragma unroll
;         for (int j = 0; j < 2; ++j) { const int idx = tid + 512 * j; rsf[j] = *(const u32x4*)((const unsigned char*)Sf + 16 * idx); rsb[j] = *(const u32x4*)((const unsigned char*)Sb + 16 * idx); }
;         OPQ_ALL();
;         bf16x8 qf[4];
; #pragma unroll
;         for (int ks = 0; ks < 4; ++ks) qf[ks] = *(const LAS bf16x8*)(Qt + off256(w16 + l15, 4 * ks + g));
;         {
;             const int n = w16 + l15;
;             f32x4 sa[8];
; #pragma unroll
;             for (int mt = 0; mt < 8; ++mt) {
;                 f32x4 a = (f32x4){0.f, 0.f, 0.f, 0.f};
; #pragma unroll
;                 for (int ks = 0; ks < 4; ++ks) a = mfma16(*(const LAS bf16x8*)(Kt + off256(16 * mt + l15, 4 * ks + g)), qf[ks], a);
;                 sa[mt] = a; }
;     ...
;         for (int t = 0; t < 8; ++t) { const int dv = 16 * t + l15; const float gn = P.rgain[h * 128 + dv];
.LBB0_384:
	s_and_b32 s57, s26, 3
	v_mov_b32_e32 v104, v216
	v_mov_b32_e32 v105, v217
	v_add_u32_e32 v50, 0, v107
	v_add_u32_e32 v51, s48, v107
	s_waitcnt vmcnt(4)
.Lp3_common:
	ds_write_b128 v50, v[6:9]
	ds_write_b128 v50, v[2:5] offset:32768
	ds_write_b128 v51, v[10:13]
	v_add_u32_e32 v51, 0, v109
	s_ashr_i32 s27, s26, 31
	s_ashr_i32 s40, s26, 2
	ds_write_b128 v51, v[14:17]
	ds_write_b128 v51, v[22:25] offset:32768
	v_add_u32_e32 v51, s48, v109
	s_lshl_b64 s[0:1], s[26:27], 16
	ds_write_b128 v51, v[18:21]
	ds_write_b128 v50, v[30:33] offset:16384
	ds_write_b128 v50, v[26:29] offset:49152
	ds_write_b128 v127, v[34:37]
	v_add_u32_e32 v50, 0, v111
	s_add_u32 s0, s44, s0
	ds_write_b128 v50, v[38:41]
	ds_write_b128 v50, v[46:49] offset:32768
	v_add_u32_e32 v50, s48, v111
	s_addc_u32 s1, s45, s1
	ds_write_b128 v50, v[42:45]
	v_lshl_add_u64 v[50:51], s[0:1], 0, v[116:117]
	v_add_co_u32_e32 v52, vcc, s47, v50
	s_waitcnt lgkmcnt(0)
	s_barrier
	v_lshl_add_u32 v214, s57, 7, v1
	v_ashrrev_i32_e32 v215, 31, v214
	v_lshl_add_u64 v[214:215], v[214:215], 2, s[62:63]
	global_load_dword v205, v[214:215], off
	global_load_dword v206, v[214:215], off offset:64
	global_load_dword v207, v[214:215], off offset:128
	global_load_dword v208, v[214:215], off offset:192
	global_load_dword v209, v[214:215], off offset:256
	global_load_dword v210, v[214:215], off offset:320
	global_load_dword v211, v[214:215], off offset:384
	global_load_dword v212, v[214:215], off offset:448
	s_cmpk_lt_i32 s40, 0x200
	s_nop 0
	v_addc_co_u32_e32 v53, vcc, 0, v51, vcc
	global_load_dwordx4 v[68:71], v[50:51], off
	global_load_dwordx4 v[76:79], v[52:53], off
	v_add_co_u32_e32 v52, vcc, s49, v50
	v_mul_f32_e32 v104, 0x3fb8aa3b, v104
	s_nop 0
	v_addc_co_u32_e32 v53, vcc, 0, v51, vcc
	v_add_co_u32_e32 v50, vcc, s50, v50
	v_mul_f32_e32 v105, 0x3fb8aa3b, v105
	s_nop 0
	v_addc_co_u32_e32 v51, vcc, 0, v51, vcc
	global_load_dwordx4 v[84:87], v[52:53], off
	global_load_dwordx4 v[92:95], v[50:51], off
	v_exp_f32_e32 v104, v104
	v_lshlrev_b32_e32 v50, 2, v1
	v_add_u32_e32 v119, s46, v1
	v_and_b32_e32 v66, 12, v50
	v_bfe_u32 v67, v1, 2, 2
	v_lshlrev_b32_e32 v135, 8, v119
	v_bitop3_b32 v50, v66, v118, v67 bitop3:0x36
	v_add_u32_e32 v52, 4, v118
	v_add_u32_e32 v100, 0, v135
	v_lshlrev_b32_e32 v50, 4, v50
	v_bitop3_b32 v52, v66, v52, v67 bitop3:0x36
	v_add_u32_e32 v51, v100, v50
	v_lshlrev_b32_e32 v72, 4, v52
	v_add_u32_e32 v52, v100, v72
	ds_read_b128 v[58:61], v51
	ds_read_b128 v[54:57], v52
	v_add_u32_e32 v51, 8, v118
	v_lshl_add_u32 v122, v1, 8, 0
	v_bitop3_b32 v51, v66, v51, v67 bitop3:0x36
	v_add_u32_e32 v156, v122, v50
	v_lshlrev_b32_e32 v80, 4, v51
	ds_read_b128 v[50:53], v156 offset:32768
	v_add_u32_e32 v157, v122, v72
	ds_read_b128 v[72:75], v157 offset:32768
	v_add_u32_e32 v62, v100, v80
	ds_read_b128 v[62:65], v62
	s_waitcnt lgkmcnt(2)
	v_mfma_f32_16x16x32_bf16 v[50:53], v[50:53], v[58:61], 0
	v_add_u32_e32 v158, v122, v80
	v_add_u32_e32 v96, 12, v118
	ds_read_b128 v[80:83], v158 offset:32768
	ds_read_b128 v[88:91], v156 offset:36864
	s_waitcnt lgkmcnt(3)
	v_mfma_f32_16x16x32_bf16 v[72:75], v[72:75], v[54:57], v[50:53]
	v_bitop3_b32 v96, v66, v96, v67 bitop3:0x36
	v_lshlrev_b32_e32 v123, 4, v96
	ds_read_b128 v[96:99], v157 offset:36864
	v_add_u32_e32 v50, v100, v123
	v_add_u32_e32 v159, v122, v123
	ds_read_b128 v[50:53], v50
	ds_read_b128 v[100:103], v158 offset:36864
	s_waitcnt lgkmcnt(4)
	v_mfma_f32_16x16x32_bf16 v[72:75], v[80:83], v[62:65], v[72:75]
	ds_read_b128 v[80:83], v159 offset:32768
	ds_read_b128 v[122:125], v159 offset:36864
	s_waitcnt lgkmcnt(1)
	v_mfma_f32_16x16x32_bf16 v[136:139], v[80:83], v[50:53], v[72:75]
	v_mfma_f32_16x16x32_bf16 v[72:75], v[88:91], v[58:61], 0
	v_mfma_f32_16x16x32_bf16 v[72:75], v[96:99], v[54:57], v[72:75]
	v_mfma_f32_16x16x32_bf16 v[72:75], v[100:103], v[62:65], v[72:75]
	s_waitcnt lgkmcnt(0)
	v_mfma_f32_16x16x32_bf16 v[122:125], v[122:125], v[50:53], v[72:75]
	s_nop 5
	ds_read_b128 v[72:75], v156 offset:40960
	ds_read_b128 v[80:83], v156 offset:45056
	ds_read_b128 v[88:91], v157 offset:40960
	ds_read_b128 v[96:99], v157 offset:45056
	s_waitcnt lgkmcnt(3)
	v_mfma_f32_16x16x32_bf16 v[72:75], v[72:75], v[58:61], 0
	s_waitcnt lgkmcnt(1)
	v_mfma_f32_16x16x32_bf16 v[72:75], v[88:91], v[54:57], v[72:75]
	ds_read_b128 v[88:91], v158 offset:40960
	ds_read_b128 v[100:103], v158 offset:45056
	s_waitcnt lgkmcnt(1)
	v_mfma_f32_16x16x32_bf16 v[72:75], v[88:91], v[62:65], v[72:75]
	ds_read_b128 v[88:91], v159 offset:40960
	ds_read_b128 v[140:143], v159 offset:45056
	s_waitcnt lgkmcnt(1)
	v_mfma_f32_16x16x32_bf16 v[144:147], v[88:91], v[50:53], v[72:75]
	v_mfma_f32_16x16x32_bf16 v[72:75], v[80:83], v[58:61], 0
	v_mfma_f32_16x16x32_bf16 v[72:75], v[96:99], v[54:57], v[72:75]
	v_mfma_f32_16x16x32_bf16 v[72:75], v[100:103], v[62:65], v[72:75]
	s_waitcnt lgkmcnt(0)
	v_mfma_f32_16x16x32_bf16 v[100:103], v[140:143], v[50:53], v[72:75]
	s_nop 5
	ds_read_b128 v[72:75], v156 offset:49152
	ds_read_b128 v[80:83], v156 offset:53248
	ds_read_b128 v[88:91], v157 offset:49152
	ds_read_b128 v[140:143], v157 offset:53248
	s_waitcnt lgkmcnt(3)
	v_mfma_f32_16x16x32_bf16 v[72:75], v[72:75], v[58:61], 0
	s_waitcnt lgkmcnt(1)
	v_mfma_f32_16x16x32_bf16 v[72:75], v[88:91], v[54:57], v[72:75]
	ds_read_b128 v[88:91], v158 offset:49152
	ds_read_b128 v[148:151], v158 offset:53248
	s_waitcnt lgkmcnt(1)
	v_mfma_f32_16x16x32_bf16 v[72:75], v[88:91], v[62:65], v[72:75]
	ds_read_b128 v[88:91], v159 offset:49152
	ds_read_b128 v[152:155], v159 offset:53248
	s_waitcnt lgkmcnt(1)
; __device__ __forceinline__ unsigned cvt_pk_bf16(float lo, float hi) { unsigned r; asm volatile("v_cvt_pk_bf16_f32 %0, %1, %2" : "=v"(r) : "v"(lo), "v"(hi)); return r; }
; #define LAS __attribute__((address_space(3)))
; __device__ __forceinline__ void ret_phase(const Params& P, LAS unsigned char* lds, int tid, int lane, int wave, int bid, int G) {
;     ...
; #pragma unroll
;             for (int mt = 0; mt < 8; ++mt) {
;                 const f32x4 a = sa[mt];
;                 float e[4];
; #pragma unroll
;                 for (int i = 0; i < 4; ++i) { const int m = 16 * mt + 4 * g + i, df = n - m; const float f = __builtin_amdgcn_exp2f(df >= 0 ? lgf2 * (float)df : lgb2 * (float)(-df)); e[i] = a[i] * f; }
;                 u32x2 w; w.x = cvt_pk_bf16(e[0], e[1]); w.y = cvt_pk_bf16(e[2], e[3]);
;                 *(LAS u32x2*)(Pt + off256(n, 2 * mt + (g >> 1)) + 8 * (g & 1)) = w;
;             }
	v_mfma_f32_16x16x32_bf16 v[96:99], v[88:91], v[50:53], v[72:75]
	v_mfma_f32_16x16x32_bf16 v[72:75], v[80:83], v[58:61], 0
	v_mfma_f32_16x16x32_bf16 v[72:75], v[140:143], v[54:57], v[72:75]
	v_mfma_f32_16x16x32_bf16 v[72:75], v[148:151], v[62:65], v[72:75]
	s_waitcnt lgkmcnt(0)
	v_mfma_f32_16x16x32_bf16 v[88:91], v[152:155], v[50:53], v[72:75]
	s_nop 5
	ds_read_b128 v[72:75], v156 offset:57344
	ds_read_b128 v[140:143], v156 offset:61440
	ds_read_b128 v[80:83], v157 offset:57344
	ds_read_b128 v[148:151], v157 offset:61440
	s_waitcnt lgkmcnt(3)
	v_mfma_f32_16x16x32_bf16 v[72:75], v[72:75], v[58:61], 0
	s_waitcnt lgkmcnt(1)
	v_mfma_f32_16x16x32_bf16 v[72:75], v[80:83], v[54:57], v[72:75]
	ds_read_b128 v[80:83], v158 offset:57344
	ds_read_b128 v[152:155], v158 offset:61440
	s_waitcnt lgkmcnt(1)
	v_mfma_f32_16x16x32_bf16 v[72:75], v[80:83], v[62:65], v[72:75]
	ds_read_b128 v[80:83], v159 offset:57344
	ds_read_b128 v[156:159], v159 offset:61440
	s_waitcnt lgkmcnt(1)
	v_mfma_f32_16x16x32_bf16 v[80:83], v[80:83], v[50:53], v[72:75]
	v_mfma_f32_16x16x32_bf16 v[72:75], v[140:143], v[58:61], 0
	v_lshlrev_b32_e32 v142, 2, v118
	v_sub_u32_e32 v143, v119, v142
	v_exp_f32_e32 v140, v105
	v_mfma_f32_16x16x32_bf16 v[72:75], v[148:151], v[54:57], v[72:75]
	v_sub_u32_e32 v148, 0, v143
	v_max_i32_e32 v148, v143, v148
	v_cvt_f32_u32_e32 v148, v148
	v_lshlrev_b32_e32 v141, 3, v118
	v_mul_f32_e32 v105, 0xbfb8aa3b, v104
	v_mul_f32_e32 v104, 0xbfb8aa3b, v140
	v_and_b32_e32 v141, 8, v141
	v_cmp_gt_i32_e32 vcc, 0, v143
	v_add3_u32 v135, s51, v135, v141
	v_lshrrev_b32_e32 v140, 1, v118
	v_cndmask_b32_e32 v141, v105, v104, vcc
	v_mul_f32_e32 v141, v141, v148
	v_xad_u32 v148, v142, -1, v119
	v_sub_u32_e32 v149, 0, v148
	v_max_i32_e32 v149, v148, v149
	v_cvt_f32_u32_e32 v149, v149
	v_cmp_gt_i32_e32 vcc, 0, v148
	v_exp_f32_e32 v141, v141
	v_mfma_f32_16x16x32_bf16 v[72:75], v[152:155], v[62:65], v[72:75]
	v_cndmask_b32_e32 v148, v105, v104, vcc
	v_mul_f32_e32 v148, v148, v149
	v_or_b32_e32 v149, 2, v142
	v_or_b32_e32 v142, 3, v142
	v_sub_u32_e32 v149, v119, v149
	v_sub_u32_e32 v119, v119, v142
	v_sub_u32_e32 v142, 0, v119
	v_sub_u32_e32 v150, 0, v149
	v_max_i32_e32 v142, v119, v142
	v_max_i32_e32 v150, v149, v150
	v_cvt_f32_u32_e32 v142, v142
	v_cvt_f32_u32_e32 v150, v150
	v_cmp_gt_i32_e32 vcc, 0, v149
	v_exp_f32_e32 v148, v148
	v_mul_f32_e32 v136, v141, v136
	v_cndmask_b32_e32 v149, v105, v104, vcc
	v_cmp_gt_i32_e32 vcc, 0, v119
	v_mul_f32_e32 v149, v149, v150
	v_exp_f32_e32 v149, v149
	v_cndmask_b32_e32 v119, v105, v104, vcc
	v_mul_f32_e32 v119, v119, v142
	v_exp_f32_e32 v119, v119
	v_mul_f32_e32 v137, v148, v137
	v_mul_f32_e32 v138, v149, v138
	v_cvt_pk_bf16_f32 v136, v136, v137
	v_mul_f32_e32 v119, v119, v139
	v_cvt_pk_bf16_f32 v137, v138, v119
	v_bitop3_b32 v119, v66, v140, v67 bitop3:0x36
	v_lshl_add_u32 v119, v119, 4, v135
	ds_write_b64 v119, v[136:137]
	v_subrev_u32_e32 v136, 17, v143
	v_sub_u32_e32 v137, 17, v143
	v_max_i32_e32 v137, v136, v137
	v_add_u32_e32 v138, -16, v143
	v_cvt_f32_u32_e32 v137, v137
	v_cmp_gt_i32_e32 vcc, 0, v138
	v_sub_u32_e32 v139, 16, v143
	v_max_i32_e32 v139, v138, v139
	v_cndmask_b32_e32 v119, v105, v104, vcc
	v_cmp_gt_i32_e32 vcc, 0, v136
	v_sub_u32_e32 v138, 18, v143
	v_cvt_f32_u32_e32 v139, v139
	v_cndmask_b32_e32 v136, v105, v104, vcc
	v_mul_f32_e32 v136, v136, v137
	v_subrev_u32_e32 v137, 18, v143
	v_max_i32_e32 v138, v137, v138
	v_cvt_f32_u32_e32 v138, v138
	v_cmp_gt_i32_e32 vcc, 0, v137
	v_mul_f32_e32 v119, v119, v139
	v_sub_u32_e32 v139, 19, v143
	v_cndmask_b32_e32 v137, v105, v104, vcc
	v_mul_f32_e32 v137, v137, v138
	v_subrev_u32_e32 v138, 19, v143
	v_max_i32_e32 v139, v138, v139
	v_cvt_f32_u32_e32 v139, v139
	v_exp_f32_e32 v119, v119
	v_exp_f32_e32 v136, v136
	v_cmp_gt_i32_e32 vcc, 0, v138
	v_exp_f32_e32 v137, v137
	v_mul_f32_e32 v119, v119, v122
	v_cndmask_b32_e32 v138, v105, v104, vcc
	v_mul_f32_e32 v138, v138, v139
	v_exp_f32_e32 v138, v138
	v_mul_f32_e32 v122, v136, v123
	v_cvt_pk_bf16_f32 v122, v119, v122
	v_add_u32_e32 v119, 2, v140
	v_mul_f32_e32 v123, v137, v124
	v_bitop3_b32 v119, v66, v119, v67 bitop3:0x36
	v_mul_f32_e32 v124, v138, v125
	v_cvt_pk_bf16_f32 v123, v123, v124
	v_lshl_add_u32 v119, v119, 4, v135
	ds_write_b64 v119, v[122:123]
	v_subrev_u32_e32 v122, 33, v143
	v_sub_u32_e32 v123, 33, v143
	v_max_i32_e32 v123, v122, v123
	v_subrev_u32_e32 v124, 32, v143
	v_cvt_f32_u32_e32 v123, v123
	v_cmp_gt_i32_e32 vcc, 0, v124
	v_sub_u32_e32 v125, 32, v143
	v_max_i32_e32 v125, v124, v125
	v_cndmask_b32_e32 v119, v105, v104, vcc
	v_cmp_gt_i32_e32 vcc, 0, v122
	v_sub_u32_e32 v124, 34, v143
	v_cvt_f32_u32_e32 v125, v125
	v_cndmask_b32_e32 v122, v105, v104, vcc
	v_mul_f32_e32 v122, v122, v123
	v_subrev_u32_e32 v123, 34, v143
	v_max_i32_e32 v124, v123, v124
	v_cvt_f32_u32_e32 v124, v124
	v_cmp_gt_i32_e32 vcc, 0, v123
	v_mul_f32_e32 v119, v119, v125
	v_sub_u32_e32 v125, 35, v143
	v_cndmask_b32_e32 v123, v105, v104, vcc
	v_mul_f32_e32 v123, v123, v124
	v_subrev_u32_e32 v124, 35, v143
	v_max_i32_e32 v125, v124, v125
	v_cvt_f32_u32_e32 v125, v125
	v_exp_f32_e32 v119, v119
	v_exp_f32_e32 v122, v122
	v_cmp_gt_i32_e32 vcc, 0, v124
	v_exp_f32_e32 v123, v123
	v_mul_f32_e32 v119, v119, v144
	v_cndmask_b32_e32 v124, v105, v104, vcc
	v_mul_f32_e32 v124, v124, v125
	v_exp_f32_e32 v124, v124
	v_mul_f32_e32 v122, v122, v145
	v_cvt_pk_bf16_f32 v122, v119, v122
	v_add_u32_e32 v119, 4, v140
	v_mul_f32_e32 v123, v123, v146
	v_bitop3_b32 v119, v66, v119, v67 bitop3:0x36
	v_mul_f32_e32 v124, v124, v147
	v_cvt_pk_bf16_f32 v123, v123, v124
	v_lshl_add_u32 v119, v119, 4, v135
	ds_write_b64 v119, v[122:123]
	v_subrev_u32_e32 v122, 49, v143
; __device__ __forceinline__ unsigned cvt_pk_bf16(float lo, float hi) { unsigned r; asm volatile("v_cvt_pk_bf16_f32 %0, %1, %2" : "=v"(r) : "v"(lo), "v"(hi)); return r; }
; #define LAS __attribute__((address_space(3)))
; #define LBAR() asm volatile("s_waitcnt lgkmcnt(0)\n\ts_barrier" ::: "memory")
; __device__ __forceinline__ void ret_phase(const Params& P, LAS unsigned char* lds, int tid, int lane, int wave, int bid, int G) {
;     ...
;             for (int mt = 0; mt < 8; ++mt) {
;                 const f32x4 a = sa[mt];
;                 float e[4];
; #pragma unroll
;                 for (int i = 0; i < 4; ++i) { const int m = 16 * mt + 4 * g + i, df = n - m; const float f = __builtin_amdgcn_exp2f(df >= 0 ? lgf2 * (float)df : lgb2 * (float)(-df)); e[i] = a[i] * f; }
;                 u32x2 w; w.x = cvt_pk_bf16(e[0], e[1]); w.y = cvt_pk_bf16(e[2], e[3]);
;                 *(LAS u32x2*)(Pt + off256(n, 2 * mt + (g >> 1)) + 8 * (g & 1)) = w;
;             }
;         }
;         LBAR();
;         u32x4 sfr[4], sbr[4];
; #pragma unroll
;         for (int j = 0; j < 2; ++j) { sfr[2 * j] = fp8x8_to_bf16x8(rsf[j].x, rsf[j].y); sfr[2 * j + 1] = fp8x8_to_bf16x8(rsf[j].z, rsf[j].w);
;             sbr[2 * j] = fp8x8_to_bf16x8(rsb[j].x, rsb[j].y); sbr[2 * j + 1] = fp8x8_to_bf16x8(rsb[j].z, rsb[j].w); }
	v_sub_u32_e32 v123, 49, v143
	v_max_i32_e32 v123, v122, v123
	v_subrev_u32_e32 v124, 48, v143
	v_cvt_f32_u32_e32 v123, v123
	v_cmp_gt_i32_e32 vcc, 0, v124
	v_sub_u32_e32 v125, 48, v143
	v_max_i32_e32 v125, v124, v125
	v_cndmask_b32_e32 v119, v105, v104, vcc
	v_cmp_gt_i32_e32 vcc, 0, v122
	v_sub_u32_e32 v124, 50, v143
	v_cvt_f32_u32_e32 v125, v125
	v_cndmask_b32_e32 v122, v105, v104, vcc
	v_mul_f32_e32 v122, v122, v123
	v_subrev_u32_e32 v123, 50, v143
	v_max_i32_e32 v124, v123, v124
	v_cvt_f32_u32_e32 v124, v124
	v_cmp_gt_i32_e32 vcc, 0, v123
	v_mul_f32_e32 v119, v119, v125
	v_sub_u32_e32 v125, 51, v143
	v_cndmask_b32_e32 v123, v105, v104, vcc
	v_mul_f32_e32 v123, v123, v124
	v_subrev_u32_e32 v124, 51, v143
	v_max_i32_e32 v125, v124, v125
	v_cvt_f32_u32_e32 v125, v125
	v_cmp_gt_i32_e32 vcc, 0, v124
	v_exp_f32_e32 v119, v119
	v_exp_f32_e32 v122, v122
	v_cndmask_b32_e32 v124, v105, v104, vcc
	v_exp_f32_e32 v123, v123
	v_mul_f32_e32 v124, v124, v125
	v_exp_f32_e32 v124, v124
	v_mul_f32_e32 v100, v119, v100
	v_mul_f32_e32 v101, v122, v101
	v_mul_f32_e32 v102, v123, v102
	v_mul_f32_e32 v103, v124, v103
	v_cvt_pk_bf16_f32 v100, v100, v101
	v_cvt_pk_bf16_f32 v101, v102, v103
	v_add_u32_e32 v102, 6, v140
	v_bitop3_b32 v102, v66, v102, v67 bitop3:0x36
	v_lshl_add_u32 v102, v102, 4, v135
	ds_write_b64 v102, v[100:101]
	v_add_u32_e32 v101, 0xffffffbf, v143
	v_sub_u32_e32 v102, 0x41, v143
	v_max_i32_e32 v102, v101, v102
	v_subrev_u32_e32 v103, 64, v143
	v_cvt_f32_u32_e32 v102, v102
	v_cmp_gt_i32_e32 vcc, 0, v103
	v_sub_u32_e32 v119, 64, v143
	v_max_i32_e32 v119, v103, v119
	v_cndmask_b32_e32 v100, v105, v104, vcc
	v_cmp_gt_i32_e32 vcc, 0, v101
	v_sub_u32_e32 v103, 0x42, v143
	v_cvt_f32_u32_e32 v119, v119
	v_cndmask_b32_e32 v101, v105, v104, vcc
	v_mul_f32_e32 v101, v101, v102
	v_add_u32_e32 v102, 0xffffffbe, v143
	v_max_i32_e32 v103, v102, v103
	v_cvt_f32_u32_e32 v103, v103
	v_cmp_gt_i32_e32 vcc, 0, v102
	v_mul_f32_e32 v100, v100, v119
	v_sub_u32_e32 v119, 0x43, v143
	v_cndmask_b32_e32 v102, v105, v104, vcc
	v_mul_f32_e32 v102, v102, v103
	v_add_u32_e32 v103, 0xffffffbd, v143
	v_max_i32_e32 v119, v103, v119
	v_cvt_f32_u32_e32 v119, v119
	v_cmp_gt_i32_e32 vcc, 0, v103
	v_exp_f32_e32 v100, v100
	v_exp_f32_e32 v101, v101
	v_cndmask_b32_e32 v103, v105, v104, vcc
	v_exp_f32_e32 v102, v102
	v_mul_f32_e32 v103, v103, v119
	v_exp_f32_e32 v103, v103
	v_mul_f32_e32 v96, v100, v96
	v_mul_f32_e32 v97, v101, v97
	v_mul_f32_e32 v98, v102, v98
	v_mul_f32_e32 v99, v103, v99
	v_cvt_pk_bf16_f32 v96, v96, v97
	v_cvt_pk_bf16_f32 v97, v98, v99
	v_add_u32_e32 v98, 8, v140
	v_bitop3_b32 v98, v66, v98, v67 bitop3:0x36
	v_lshl_add_u32 v98, v98, 4, v135
	ds_write_b64 v98, v[96:97]
	v_add_u32_e32 v97, 0xffffffaf, v143
	v_sub_u32_e32 v98, 0x51, v143
	v_max_i32_e32 v98, v97, v98
	v_add_u32_e32 v99, 0xffffffb0, v143
	v_cvt_f32_u32_e32 v98, v98
	v_cmp_gt_i32_e32 vcc, 0, v99
	v_sub_u32_e32 v100, 0x50, v143
	v_max_i32_e32 v100, v99, v100
	v_cndmask_b32_e32 v96, v105, v104, vcc
	v_cmp_gt_i32_e32 vcc, 0, v97
	v_sub_u32_e32 v99, 0x52, v143
	v_cvt_f32_u32_e32 v100, v100
	v_cndmask_b32_e32 v97, v105, v104, vcc
	v_mul_f32_e32 v97, v97, v98
	v_add_u32_e32 v98, 0xffffffae, v143
	v_max_i32_e32 v99, v98, v99
	v_cvt_f32_u32_e32 v99, v99
	v_cmp_gt_i32_e32 vcc, 0, v98
	v_mul_f32_e32 v96, v96, v100
	v_sub_u32_e32 v100, 0x53, v143
	v_cndmask_b32_e32 v98, v105, v104, vcc
	v_mul_f32_e32 v98, v98, v99
	v_add_u32_e32 v99, 0xffffffad, v143
	v_max_i32_e32 v100, v99, v100
	v_cvt_f32_u32_e32 v100, v100
	v_cmp_gt_i32_e32 vcc, 0, v99
	v_exp_f32_e32 v96, v96
	v_exp_f32_e32 v97, v97
	v_cndmask_b32_e32 v99, v105, v104, vcc
	v_exp_f32_e32 v98, v98
	v_mul_f32_e32 v99, v99, v100
	v_exp_f32_e32 v99, v99
	v_mul_f32_e32 v88, v96, v88
	v_mul_f32_e32 v89, v97, v89
	v_mul_f32_e32 v90, v98, v90
	v_mul_f32_e32 v91, v99, v91
	v_cvt_pk_bf16_f32 v88, v88, v89
	v_cvt_pk_bf16_f32 v89, v90, v91
	v_add_u32_e32 v90, 10, v140
	v_bitop3_b32 v90, v66, v90, v67 bitop3:0x36
	v_lshl_add_u32 v90, v90, 4, v135
	ds_write_b64 v90, v[88:89]
	v_add_u32_e32 v89, 0xffffff9f, v143
	v_sub_u32_e32 v90, 0x61, v143
	v_max_i32_e32 v90, v89, v90
	v_add_u32_e32 v91, 0xffffffa0, v143
	v_cvt_f32_u32_e32 v90, v90
	v_cmp_gt_i32_e32 vcc, 0, v91
	v_sub_u32_e32 v96, 0x60, v143
	v_max_i32_e32 v96, v91, v96
	v_cndmask_b32_e32 v88, v105, v104, vcc
	v_cmp_gt_i32_e32 vcc, 0, v89
	v_sub_u32_e32 v91, 0x62, v143
	v_cvt_f32_u32_e32 v96, v96
	v_cndmask_b32_e32 v89, v105, v104, vcc
	v_mul_f32_e32 v89, v89, v90
	v_add_u32_e32 v90, 0xffffff9e, v143
	v_max_i32_e32 v91, v90, v91
	v_cvt_f32_u32_e32 v91, v91
	v_cmp_gt_i32_e32 vcc, 0, v90
	v_mul_f32_e32 v88, v88, v96
	v_sub_u32_e32 v96, 0x63, v143
	v_cndmask_b32_e32 v90, v105, v104, vcc
	v_mul_f32_e32 v90, v90, v91
	v_add_u32_e32 v91, 0xffffff9d, v143
	v_max_i32_e32 v96, v91, v96
	v_cvt_f32_u32_e32 v96, v96
	v_cmp_gt_i32_e32 vcc, 0, v91
	v_exp_f32_e32 v88, v88
	v_exp_f32_e32 v89, v89
	v_cndmask_b32_e32 v91, v105, v104, vcc
	v_exp_f32_e32 v90, v90
	v_mul_f32_e32 v91, v91, v96
	v_exp_f32_e32 v91, v91
	v_mul_f32_e32 v80, v88, v80
	v_mul_f32_e32 v81, v89, v81
	v_mul_f32_e32 v82, v90, v82
	v_mul_f32_e32 v83, v91, v83
	v_cvt_pk_bf16_f32 v80, v80, v81
	v_cvt_pk_bf16_f32 v81, v82, v83
	v_add_u32_e32 v82, 12, v140
	v_bitop3_b32 v82, v66, v82, v67 bitop3:0x36
	v_lshl_add_u32 v82, v82, 4, v135
	ds_write_b64 v82, v[80:81]
	v_add_u32_e32 v81, 0xffffff8f, v143
	v_sub_u32_e32 v82, 0x71, v143
	v_max_i32_e32 v82, v81, v82
	v_add_u32_e32 v83, 0xffffff90, v143
	v_cvt_f32_u32_e32 v82, v82
	v_cmp_gt_i32_e32 vcc, 0, v83
	v_sub_u32_e32 v88, 0x70, v143
	v_max_i32_e32 v88, v83, v88
	v_cndmask_b32_e32 v80, v105, v104, vcc
	v_cmp_gt_i32_e32 vcc, 0, v81
	v_sub_u32_e32 v83, 0x72, v143
	v_cvt_f32_u32_e32 v88, v88
	v_cndmask_b32_e32 v81, v105, v104, vcc
	v_mul_f32_e32 v81, v81, v82
	v_add_u32_e32 v82, 0xffffff8e, v143
	v_max_i32_e32 v83, v82, v83
	v_cvt_f32_u32_e32 v83, v83
	v_cmp_gt_i32_e32 vcc, 0, v82
	v_mul_f32_e32 v80, v80, v88
	v_sub_u32_e32 v88, 0x73, v143
	v_cndmask_b32_e32 v82, v105, v104, vcc
	v_mul_f32_e32 v82, v82, v83
	v_add_u32_e32 v83, 0xffffff8d, v143
	v_max_i32_e32 v88, v83, v88
	v_cvt_f32_u32_e32 v88, v88
	v_cmp_gt_i32_e32 vcc, 0, v83
	s_waitcnt lgkmcnt(7)
	v_mfma_f32_16x16x32_bf16 v[72:75], v[156:159], v[50:53], v[72:75]
	v_exp_f32_e32 v80, v80
	v_cndmask_b32_e32 v83, v105, v104, vcc
	v_exp_f32_e32 v81, v81
	v_exp_f32_e32 v82, v82
	v_mul_f32_e32 v83, v83, v88
	v_exp_f32_e32 v83, v83
	s_nop 1
	v_mul_f32_e32 v72, v80, v72
	v_mul_f32_e32 v73, v81, v73
	v_mul_f32_e32 v74, v82, v74
	v_mul_f32_e32 v75, v83, v75
	v_cvt_pk_bf16_f32 v72, v72, v73
	v_cvt_pk_bf16_f32 v73, v74, v75
	v_add_u32_e32 v74, 14, v140
	v_bitop3_b32 v66, v66, v74, v67 bitop3:0x36
	v_lshl_add_u32 v66, v66, 4, v135
	ds_write_b64 v66, v[72:73]
	s_waitcnt vmcnt(3)
	v_cvt_pk_f32_fp8_e32 v[66:67], v68
	v_cvt_pk_f32_fp8_sdwa v[72:73], v68 src0_sel:WORD_1
	v_cvt_pk_f32_fp8_e32 v[74:75], v69
	v_cvt_pk_f32_fp8_sdwa v[80:81], v69 src0_sel:WORD_1
	s_waitcnt lgkmcnt(0)
	s_barrier
; __device__ __forceinline__ void ret_phase(const Params& P, LAS unsigned char* lds, int tid, int lane, int wave, int bid, int G) {
;     ...
;         u32x4 sfr[4], sbr[4];
; #pragma unroll
;         for (int j = 0; j < 2; ++j) { sfr[2 * j] = fp8x8_to_bf16x8(rsf[j].x, rsf[j].y); sfr[2 * j + 1] = fp8x8_to_bf16x8(rsf[j].z, rsf[j].w);
;             sbr[2 * j] = fp8x8_to_bf16x8(rsb[j].x, rsb[j].y); sbr[2 * j + 1] = fp8x8_to_bf16x8(rsb[j].z, rsb[j].w); }
;     ...
;         if (gc >= 512) {
;             const int k = (gc - 512) >> 5, j = gc & 31;
;             const float cf = exp2f(lgf2 * 128.f * (float)j), cb = exp2f(lgb2 * 128.f * (float)(31 - j)), df32 = exp2f(lgf2 * 4096.f), db32 = exp2f(lgb2 * 4096.f);
;             float wgt = cf;
	v_cvt_pk_bf16_f32 v66, v66, v67
	v_cvt_pk_bf16_f32 v67, v72, v73
	v_cvt_pk_bf16_f32 v68, v74, v75
	v_cvt_pk_bf16_f32 v69, v80, v81
	v_cvt_pk_f32_fp8_e32 v[72:73], v70
	v_cvt_pk_f32_fp8_sdwa v[74:75], v70 src0_sel:WORD_1
	v_cvt_pk_f32_fp8_e32 v[80:81], v71
	v_cvt_pk_f32_fp8_sdwa v[82:83], v71 src0_sel:WORD_1
	v_cvt_pk_bf16_f32 v70, v72, v73
	v_cvt_pk_bf16_f32 v71, v74, v75
	v_cvt_pk_bf16_f32 v72, v80, v81
	v_cvt_pk_bf16_f32 v73, v82, v83
	s_waitcnt vmcnt(2)
	v_cvt_pk_f32_fp8_e32 v[74:75], v76
	v_cvt_pk_f32_fp8_sdwa v[80:81], v76 src0_sel:WORD_1
	v_cvt_pk_f32_fp8_e32 v[82:83], v77
	v_cvt_pk_f32_fp8_sdwa v[88:89], v77 src0_sel:WORD_1
	v_cvt_pk_bf16_f32 v74, v74, v75
	v_cvt_pk_bf16_f32 v75, v80, v81
	v_cvt_pk_bf16_f32 v76, v82, v83
	v_cvt_pk_bf16_f32 v77, v88, v89
	v_cvt_pk_f32_fp8_e32 v[80:81], v78
	v_cvt_pk_f32_fp8_sdwa v[82:83], v78 src0_sel:WORD_1
	v_cvt_pk_f32_fp8_e32 v[88:89], v79
	v_cvt_pk_f32_fp8_sdwa v[90:91], v79 src0_sel:WORD_1
	v_cvt_pk_bf16_f32 v78, v80, v81
	v_cvt_pk_bf16_f32 v79, v82, v83
	v_cvt_pk_bf16_f32 v80, v88, v89
	v_cvt_pk_bf16_f32 v81, v90, v91
	s_waitcnt vmcnt(1)
	v_cvt_pk_f32_fp8_e32 v[82:83], v84
	v_cvt_pk_f32_fp8_sdwa v[88:89], v84 src0_sel:WORD_1
	v_cvt_pk_f32_fp8_e32 v[90:91], v85
	v_cvt_pk_f32_fp8_sdwa v[96:97], v85 src0_sel:WORD_1
	v_cvt_pk_bf16_f32 v82, v82, v83
	v_cvt_pk_bf16_f32 v83, v88, v89
	v_cvt_pk_bf16_f32 v84, v90, v91
	v_cvt_pk_bf16_f32 v85, v96, v97
	v_cvt_pk_f32_fp8_e32 v[88:89], v86
	v_cvt_pk_f32_fp8_sdwa v[90:91], v86 src0_sel:WORD_1
	v_cvt_pk_f32_fp8_e32 v[96:97], v87
	v_cvt_pk_f32_fp8_sdwa v[98:99], v87 src0_sel:WORD_1
	v_cvt_pk_bf16_f32 v86, v88, v89
	v_cvt_pk_bf16_f32 v87, v90, v91
	v_cvt_pk_bf16_f32 v88, v96, v97
	s_waitcnt vmcnt(0)
	v_cvt_pk_f32_fp8_e32 v[90:91], v92
	v_cvt_pk_f32_fp8_sdwa v[96:97], v92 src0_sel:WORD_1
	v_cvt_pk_bf16_f32 v89, v98, v99
	v_cvt_pk_f32_fp8_e32 v[98:99], v93
	v_cvt_pk_f32_fp8_sdwa v[100:101], v93 src0_sel:WORD_1
	v_cvt_pk_bf16_f32 v90, v90, v91
	v_cvt_pk_bf16_f32 v91, v96, v97
	v_cvt_pk_f32_fp8_e32 v[96:97], v94
	v_cvt_pk_bf16_f32 v92, v98, v99
	v_cvt_pk_bf16_f32 v93, v100, v101
	v_cvt_pk_f32_fp8_sdwa v[98:99], v94 src0_sel:WORD_1
	v_cvt_pk_f32_fp8_e32 v[100:101], v95
	v_cvt_pk_f32_fp8_sdwa v[102:103], v95 src0_sel:WORD_1
	v_cvt_pk_bf16_f32 v94, v96, v97
	v_cvt_pk_bf16_f32 v95, v98, v99
	v_cvt_pk_bf16_f32 v96, v100, v101
	v_cvt_pk_bf16_f32 v97, v102, v103
	s_cbranch_scc1 .LBB0_391
	s_add_i32 s34, s40, 0xfffffe00
	s_and_b32 s5, s56, 3
	s_lshr_b32 s4, s34, 5
	s_bfe_u32 s27, s26, 0x50002
	s_cmp_lt_u32 s34, 32
	s_cbranch_scc1 .LBB0_388
	v_mul_f32_e32 v98, 0x45800000, v105
	v_cmp_gt_f32_e32 vcc, s52, v98
	v_mul_f32_e32 v99, 0x43000000, v105
	v_cvt_f32_ubyte0_e32 v100, s27
	v_cndmask_b32_e32 v98, 0, v132, vcc
	v_mul_f32_e32 v101, v99, v100
	s_and_b64 s[0:1], vcc, exec
	v_fmac_f32_e32 v98, 0x45800000, v105
	v_cmp_gt_f32_e32 vcc, s52, v101
	v_exp_f32_e32 v98, v98
	s_cselect_b32 s0, 0xffffffc0, 0
	v_cndmask_b32_e32 v101, 0, v132, vcc
	v_fmac_f32_e32 v101, v99, v100
	v_exp_f32_e32 v99, v101
	v_ldexp_f32 v98, v98, s0
	s_and_b64 s[0:1], vcc, exec
	s_cselect_b32 s0, 0xffffffc0, 0
	v_ldexp_f32 v99, v99, s0
	s_lshl_b32 s0, s4, 2
	s_or_b32 s0, s0, s5
	s_add_i32 s18, s0, 60
	s_add_i32 s35, s4, 1

; #define LAS __attribute__((address_space(3)))
; #define RT_LOAD(u_) do { const size_t tokc_ = (size_t)((u_) >> 2) * 128; const int h_ = (u_) & 3; \
;         _Pragma("unroll") for (int i = 0; i < 4; ++i) { const int idx = tid + 512 * i; const size_t src = (tokc_ + (idx >> 4)) * 512 + h_ * 128 + 8 * (idx & 15); \
;             rq[i] = *(const u32x4*)(QR + src); rk[i] = *(const u32x4*)(KR + src); rv[i] = *(const u32x4*)(VR + src); } } while (0)
; __device__ __forceinline__ void ret_phase(const Params& P, LAS unsigned char* lds, int tid, int lane, int wave, int bid, int G) {
;     ...
;         const float lgf2 = -__expf(P.dec_f[h]) * LOG2E, lgb2 = -__expf(P.dec_b[h]) * LOG2E;
;     ...
;         for (int j = 0; j < 2; ++j) { const int idx = tid + 512 * j; const unsigned row = idx >> 3, c8 = idx & 7;
;             *(LAS u32x4*)(Qt + off256(row, 2 * c8)) = sfr[2 * j]; *(LAS u32x4*)(Qt + off256(row, 2 * c8 + 1)) = sfr[2 * j + 1];
;             *(LAS u32x4*)(Kt + off256(row, 2 * c8)) = sbr[2 * j]; *(LAS u32x4*)(Kt + off256(row, 2 * c8 + 1)) = sbr[2 * j + 1]; }
;         if (u + G < RET_UNITS) RT_LOAD(u + G);
.LBB0_391:
	s_add_i32 s26, s26, s3
	s_cmpk_gt_i32 s26, 0x9ff
	s_cselect_b64 s[42:43], -1, 0
	s_and_b64 vcc, exec, s[42:43]
	ds_write_b128 v128, v[66:69]
	ds_write_b128 v129, v[70:73]
	ds_write_b128 v128, v[74:77] offset:32768
	ds_write_b128 v129, v[78:81] offset:32768
	ds_write_b128 v130, v[82:85]
	ds_write_b128 v131, v[86:89]
	ds_write_b128 v130, v[90:93] offset:32768
	ds_write_b128 v131, v[94:97] offset:32768
	s_cbranch_vccnz .LBB0_383
	s_ashr_i32 s0, s26, 2
	s_ashr_i32 s1, s0, 31
	s_lshl_b32 s4, s26, 7
	s_lshl_b64 s[0:1], s[0:1], 16
	s_and_b32 s4, s4, 0x180
	s_or_b32 s0, s0, s4
	v_mov_b32_e32 v35, s1
	v_or_b32_e32 v34, s0, v106
	v_mov_b32_e32 v3, s1
	v_or_b32_e32 v2, v34, v108
	v_mov_b32_e32 v13, s1
	v_or_b32_e32 v12, v34, v110
	v_mov_b32_e32 v27, s1
	v_or_b32_e32 v26, v34, v112
	v_lshl_add_u64 v[34:35], v[34:35], 0, v[114:115]
	v_lshlrev_b64 v[10:11], 1, v[2:3]
	v_lshlrev_b64 v[18:19], 1, v[12:13]
	v_lshlrev_b64 v[36:37], 1, v[26:27]
	v_lshlrev_b64 v[42:43], 1, v[34:35]
	v_lshl_add_u64 v[2:3], s[10:11], 0, v[10:11]
	v_lshl_add_u64 v[4:5], s[12:13], 0, v[10:11]
	v_lshl_add_u64 v[10:11], s[14:15], 0, v[10:11]
	v_lshl_add_u64 v[14:15], s[10:11], 0, v[18:19]
	v_lshl_add_u64 v[20:21], s[12:13], 0, v[18:19]
	v_lshl_add_u64 v[18:19], s[14:15], 0, v[18:19]
	v_lshl_add_u64 v[26:27], s[10:11], 0, v[36:37]
	v_lshl_add_u64 v[28:29], s[12:13], 0, v[36:37]
	v_lshl_add_u64 v[36:37], s[14:15], 0, v[36:37]
	v_lshl_add_u64 v[38:39], s[10:11], 0, v[42:43]
	v_lshl_add_u64 v[44:45], s[12:13], 0, v[42:43]
	v_lshl_add_u64 v[42:43], s[14:15], 0, v[42:43]
	global_load_dwordx4 v[6:9], v[2:3], off
	s_nop 0
	global_load_dwordx4 v[2:5], v[4:5], off
	s_nop 0
	global_load_dwordx4 v[10:13], v[10:11], off
	s_nop 0
	global_load_dwordx4 v[14:17], v[14:15], off
	s_nop 0
	global_load_dwordx4 v[22:25], v[20:21], off
	s_nop 0
	global_load_dwordx4 v[18:21], v[18:19], off
	s_nop 0
	global_load_dwordx4 v[30:33], v[26:27], off
	s_nop 0
	global_load_dwordx4 v[26:29], v[28:29], off
	s_nop 0
	global_load_dwordx4 v[34:37], v[36:37], off
	s_nop 0
	global_load_dwordx4 v[38:41], v[38:39], off
	s_nop 0
	global_load_dwordx4 v[46:49], v[44:45], off
	s_nop 0
	global_load_dwordx4 v[42:45], v[42:43], off
	s_and_b32 s0, s26, 3
	s_lshl_b32 s0, s0, 2
	v_mov_b32_e32 v218, s0
	global_load_dword v216, v218, s[58:59]
	global_load_dword v217, v218, s[60:61]
	s_branch .LBB0_383
